# P6/P11: weight-column remap in P0 transposes so each wave owns 64 contiguous output columns; epilogue half-line stores of a line now adjacent (bj at +64B)
# speedup vs baseline: 1.0067x; 1.0011x over previous
.LBB0_31:
	s_lshl_b32 s26, s24, 1
	s_lshl_b32 s27, s4, 1
	v_mov_b32_e32 v55, v5
	v_or_b32_e32 v54, s26, v11
	v_or_b32_e32 v4, s27, v52
	s_add_i32 s62, s26, 4
	s_add_i32 s63, s27, 4
	v_mov_b32_e32 v57, v5
	s_add_i32 s64, s26, 8
	s_add_i32 s65, s27, 8
	v_lshl_add_u64 v[82:83], v[4:5], 2, s[10:11]
	v_lshl_add_u64 v[84:85], v[54:55], 2, s[10:11]
	v_lshlrev_b64 v[54:55], 14, v[54:55]
	v_lshlrev_b64 v[86:87], 14, v[4:5]
	v_or_b32_e32 v56, s62, v11
	v_or_b32_e32 v4, s63, v52
	v_mov_b32_e32 v59, v5
	s_add_i32 s66, s26, 12
	s_add_i32 s67, s27, 12
	v_or_b32_e32 v58, s64, v11
	global_load_dword v82, v[82:83], off
	s_nop 0
	global_load_dword v83, v[84:85], off
	v_lshl_add_u64 v[84:85], v[50:51], 0, v[86:87]
	v_lshl_add_u64 v[54:55], v[50:51], 0, v[54:55]
	v_lshl_add_u64 v[86:87], v[4:5], 2, s[10:11]
	v_lshl_add_u64 v[88:89], v[56:57], 2, s[10:11]
	v_lshlrev_b64 v[56:57], 14, v[56:57]
	v_lshlrev_b64 v[90:91], 14, v[4:5]
	v_or_b32_e32 v4, s65, v52
	v_mov_b32_e32 v61, v5
	s_add_i32 s68, s26, 16
	s_add_i32 s69, s27, 16
	v_or_b32_e32 v60, s66, v11
	v_lshl_add_u64 v[92:93], v[58:59], 2, s[10:11]
	v_lshlrev_b64 v[58:59], 14, v[58:59]
	global_load_dword v84, v[84:85], off
	s_nop 0
	global_load_dword v85, v[54:55], off
	s_nop 0
	global_load_dword v54, v[86:87], off
	global_load_dword v55, v[88:89], off
	v_lshl_add_u64 v[86:87], v[50:51], 0, v[90:91]
	v_lshl_add_u64 v[56:57], v[50:51], 0, v[56:57]
	v_lshl_add_u64 v[88:89], v[4:5], 2, s[10:11]
	v_lshlrev_b64 v[90:91], 14, v[4:5]
	v_or_b32_e32 v4, s67, v52
	v_mov_b32_e32 v63, v5
	s_add_i32 s70, s26, 20
	s_add_i32 s71, s27, 20
	v_or_b32_e32 v62, s68, v11
	v_lshl_add_u64 v[94:95], v[60:61], 2, s[10:11]
	v_lshlrev_b64 v[60:61], 14, v[60:61]
	v_lshl_add_u64 v[58:59], v[50:51], 0, v[58:59]
	global_load_dword v86, v[86:87], off
	s_nop 0
	global_load_dword v87, v[56:57], off
	s_nop 0
	global_load_dword v56, v[88:89], off
	global_load_dword v57, v[92:93], off
	v_lshl_add_u64 v[88:89], v[50:51], 0, v[90:91]
	v_lshl_add_u64 v[90:91], v[4:5], 2, s[10:11]
	v_lshlrev_b64 v[92:93], 14, v[4:5]
	v_or_b32_e32 v4, s69, v52
	v_mov_b32_e32 v65, v5
	s_add_i32 s72, s26, 24
	s_add_i32 s73, s27, 24
	v_or_b32_e32 v64, s70, v11
	v_lshl_add_u64 v[96:97], v[62:63], 2, s[10:11]
	v_lshlrev_b64 v[62:63], 14, v[62:63]
	v_lshl_add_u64 v[60:61], v[50:51], 0, v[60:61]
	global_load_dword v88, v[88:89], off
	s_nop 0
	global_load_dword v89, v[58:59], off
	s_nop 0
	global_load_dword v58, v[90:91], off
	global_load_dword v59, v[94:95], off
	v_lshl_add_u64 v[90:91], v[50:51], 0, v[92:93]
	v_lshl_add_u64 v[92:93], v[4:5], 2, s[10:11]
	v_lshlrev_b64 v[94:95], 14, v[4:5]
	v_or_b32_e32 v4, s71, v52
	v_mov_b32_e32 v67, v5
	s_add_i32 s75, s27, 28
	v_or_b32_e32 v66, s72, v11
	v_lshl_add_u64 v[98:99], v[64:65], 2, s[10:11]
	v_lshlrev_b64 v[64:65], 14, v[64:65]
	v_lshl_add_u64 v[62:63], v[50:51], 0, v[62:63]
	global_load_dword v90, v[90:91], off
	s_nop 0
	global_load_dword v91, v[60:61], off
	s_nop 0
	global_load_dword v60, v[92:93], off
	global_load_dword v61, v[96:97], off
	v_lshl_add_u64 v[92:93], v[50:51], 0, v[94:95]
	v_lshl_add_u64 v[94:95], v[4:5], 2, s[10:11]
	v_lshlrev_b64 v[96:97], 14, v[4:5]
	v_or_b32_e32 v4, s73, v52
	s_add_i32 s74, s26, 28
	v_lshl_add_u64 v[100:101], v[66:67], 2, s[10:11]
	v_lshlrev_b64 v[66:67], 14, v[66:67]
	v_lshl_add_u64 v[64:65], v[50:51], 0, v[64:65]
	global_load_dword v92, v[92:93], off
	s_nop 0
	global_load_dword v93, v[62:63], off
	s_nop 0
	global_load_dword v62, v[94:95], off
	global_load_dword v63, v[98:99], off
	v_lshl_add_u64 v[94:95], v[50:51], 0, v[96:97]
	v_lshl_add_u64 v[96:97], v[4:5], 2, s[10:11]
	v_lshlrev_b64 v[98:99], 14, v[4:5]
	v_or_b32_e32 v4, s75, v52
	v_mov_b32_e32 v69, v5
	v_or_b32_e32 v68, s74, v11
	v_lshl_add_u64 v[66:67], v[50:51], 0, v[66:67]
	global_load_dword v94, v[94:95], off
	s_nop 0
	global_load_dword v95, v[64:65], off
	s_nop 0
	global_load_dword v64, v[96:97], off
	global_load_dword v65, v[100:101], off
	v_lshl_add_u64 v[96:97], v[50:51], 0, v[98:99]
	v_lshl_add_u64 v[98:99], v[4:5], 2, s[10:11]
	v_lshlrev_b64 v[100:101], 14, v[4:5]
	v_lshl_add_u64 v[102:103], v[68:69], 2, s[10:11]
	v_lshlrev_b64 v[68:69], 14, v[68:69]
	global_load_dword v96, v[96:97], off
	s_nop 0
	global_load_dword v97, v[66:67], off
	s_nop 0
	global_load_dword v66, v[98:99], off
	global_load_dword v67, v[102:103], off
	v_lshl_add_u64 v[98:99], v[50:51], 0, v[100:101]
	v_lshl_add_u64 v[68:69], v[50:51], 0, v[68:69]
	global_load_dword v98, v[98:99], off
	s_nop 0
	global_load_dword v99, v[68:69], off
	v_or_b32_e32 v4, s26, v1
	v_or_b32_e32 v53, s27, v2
	v_mad_u64_u32 v[68:69], s[26:27], v53, s3, v[10:11]
	v_mad_u64_u32 v[100:101], s[26:27], v4, s3, v[10:11]
	v_or_b32_e32 v53, s63, v2
	v_or_b32_e32 v4, s62, v1
	v_or_b32_e32 v101, s65, v2
	v_mad_u64_u32 v[102:103], s[26:27], v53, s3, v[10:11]
	v_or_b32_e32 v69, s64, v1
	v_or_b32_e32 v110, s67, v2
	v_mad_u64_u32 v[104:105], s[26:27], v4, s3, v[10:11]
	s_waitcnt vmcnt(28)
	v_pk_mul_f32 v[82:83], v[82:83], v[84:85]
	v_mad_u64_u32 v[106:107], s[26:27], v101, s3, v[10:11]
	ds_write_b32 v68, v82
	ds_write_b32 v100, v83
	v_or_b32_e32 v112, s66, v1
	v_or_b32_e32 v114, s69, v2
	v_mad_u64_u32 v[108:109], s[26:27], v69, s3, v[10:11]
	v_mad_u64_u32 v[110:111], s[26:27], v110, s3, v[10:11]
	v_or_b32_e32 v116, s68, v1
	v_or_b32_e32 v118, s71, v2
	v_mad_u64_u32 v[112:113], s[26:27], v112, s3, v[10:11]
	s_waitcnt vmcnt(24)
	v_pk_mul_f32 v[54:55], v[54:55], v[86:87]
	ds_write_b32 v102, v54
	ds_write_b32 v104, v55
	v_mad_u64_u32 v[114:115], s[26:27], v114, s3, v[10:11]
	v_or_b32_e32 v120, s70, v1
	v_or_b32_e32 v122, s73, v2
	v_mad_u64_u32 v[116:117], s[26:27], v116, s3, v[10:11]
	v_mad_u64_u32 v[118:119], s[26:27], v118, s3, v[10:11]
	s_add_i32 s4, s4, 16
	s_waitcnt vmcnt(20)
	v_pk_mul_f32 v[54:55], v[56:57], v[88:89]
	ds_write_b32 v106, v54
	ds_write_b32 v108, v55
	s_add_i32 s24, s24, 16
	s_add_i32 s25, s25, -16
	v_or_b32_e32 v124, s72, v1
	v_or_b32_e32 v126, s75, v2
	v_mad_u64_u32 v[120:121], s[26:27], v120, s3, v[10:11]
	v_mad_u64_u32 v[122:123], s[26:27], v122, s3, v[10:11]
	v_or_b32_e32 v128, s74, v1
	s_waitcnt vmcnt(16)
	v_pk_mul_f32 v[54:55], v[58:59], v[90:91]
	ds_write_b32 v110, v54
	ds_write_b32 v112, v55
	s_cmp_lg_u32 s25, 0
	v_mad_u64_u32 v[124:125], s[26:27], v124, s3, v[10:11]
	v_mad_u64_u32 v[126:127], s[26:27], v126, s3, v[10:11]
	v_mad_u64_u32 v[128:129], s[26:27], v128, s3, v[10:11]
	s_waitcnt vmcnt(12)
	v_pk_mul_f32 v[54:55], v[60:61], v[92:93]
	ds_write_b32 v114, v54
	ds_write_b32 v116, v55
	s_waitcnt vmcnt(8)
	v_pk_mul_f32 v[54:55], v[62:63], v[94:95]
	ds_write_b32 v118, v54
	ds_write_b32 v120, v55
	s_waitcnt vmcnt(4)
	v_pk_mul_f32 v[54:55], v[64:65], v[96:97]
	ds_write_b32 v122, v54
	ds_write_b32 v124, v55
	s_waitcnt vmcnt(0)
	v_pk_mul_f32 v[54:55], v[66:67], v[98:99]
	ds_write_b32 v126, v54
	ds_write_b32 v128, v55
	s_cbranch_scc1 .LBB0_31
	s_waitcnt lgkmcnt(0)
	ds_read2_b32 v[50:51], v70 offset1:33
	s_waitcnt lgkmcnt(0)
	v_cvt_pk_bf16_f32 v50, v50, v51
	ds_read2_b32 v[52:53], v70 offset0:66 offset1:99
	s_lshl_b32 s4, s1, 1
	s_bfe_u32 s98, s0, 0x10005
	s_bfe_u32 s99, s0, 0x20006
	s_lshl_b32 s98, s98, 7
	s_lshl_b32 s99, s99, 5
	s_or_b32 s98, s98, s99
	s_andn2_b32 s99, s0, 0xe0
	s_or_b32 s98, s98, s99
	v_or_b32_e32 v4, s98, v45
	s_waitcnt lgkmcnt(0)
	v_cvt_pk_bf16_f32 v51, v52, v53
	ds_read2_b32 v[52:53], v70 offset0:132 offset1:165
	v_lshl_add_u64 v[56:57], v[18:19], 0, s[4:5]
	v_lshlrev_b32_e32 v4, 11, v4
	s_waitcnt lgkmcnt(0)
	v_cvt_pk_bf16_f32 v52, v52, v53
	ds_read2_b32 v[54:55], v70 offset0:198 offset1:231
	s_waitcnt lgkmcnt(0)
	v_cvt_pk_bf16_f32 v53, v54, v55
	v_lshl_add_u64 v[58:59], v[56:57], 0, v[4:5]
	ds_read2_b32 v[54:55], v70 offset0:8 offset1:41
	global_store_dwordx4 v[58:59], v[50:53], off
	v_or_b32_e32 v4, s98, v71
	v_lshlrev_b32_e32 v4, 11, v4
	s_waitcnt lgkmcnt(0)
	v_cvt_pk_bf16_f32 v50, v54, v55
	ds_read2_b32 v[52:53], v70 offset0:74 offset1:107
	s_waitcnt lgkmcnt(0)
	v_cvt_pk_bf16_f32 v51, v52, v53
	ds_read2_b32 v[52:53], v70 offset0:140 offset1:173
	s_waitcnt lgkmcnt(0)
	v_cvt_pk_bf16_f32 v52, v52, v53
	ds_read2_b32 v[54:55], v70 offset0:206 offset1:239
	s_waitcnt lgkmcnt(0)
	v_cvt_pk_bf16_f32 v53, v54, v55
	v_lshl_add_u64 v[58:59], v[56:57], 0, v[4:5]
	ds_read2_b32 v[54:55], v70 offset0:16 offset1:49
	global_store_dwordx4 v[58:59], v[50:53], off
	v_or_b32_e32 v4, s98, v72
	v_lshlrev_b32_e32 v4, 11, v4
	s_waitcnt lgkmcnt(0)
	v_cvt_pk_bf16_f32 v50, v54, v55
	ds_read2_b32 v[52:53], v70 offset0:82 offset1:115
	s_waitcnt lgkmcnt(0)
	v_cvt_pk_bf16_f32 v51, v52, v53
	ds_read2_b32 v[52:53], v70 offset0:148 offset1:181
	s_waitcnt lgkmcnt(0)
	v_cvt_pk_bf16_f32 v52, v52, v53
	ds_read2_b32 v[54:55], v70 offset0:214 offset1:247
	s_waitcnt lgkmcnt(0)
	v_cvt_pk_bf16_f32 v53, v54, v55
	v_lshl_add_u64 v[58:59], v[56:57], 0, v[4:5]
	ds_read2_b32 v[54:55], v70 offset0:24 offset1:57
	global_store_dwordx4 v[58:59], v[50:53], off
	v_or_b32_e32 v4, s98, v73
	v_lshlrev_b32_e32 v4, 11, v4
	s_waitcnt lgkmcnt(0)
	v_cvt_pk_bf16_f32 v50, v54, v55
	ds_read2_b32 v[52:53], v70 offset0:90 offset1:123
	s_waitcnt lgkmcnt(0)
	v_cvt_pk_bf16_f32 v51, v52, v53
	ds_read2_b32 v[52:53], v70 offset0:156 offset1:189
	s_waitcnt lgkmcnt(0)
	v_cvt_pk_bf16_f32 v52, v52, v53
	ds_read2_b32 v[54:55], v70 offset0:222 offset1:255
	s_waitcnt lgkmcnt(0)
	v_cvt_pk_bf16_f32 v53, v54, v55
	v_lshl_add_u64 v[54:55], v[56:57], 0, v[4:5]
	global_store_dwordx4 v[54:55], v[50:53], off
	s_waitcnt lgkmcnt(0)

.LBB0_68:
	s_waitcnt lgkmcnt(0)
	s_add_i32 s0, s49, 0xfffffa20
	s_lshl_b32 s1, s0, 5
	ds_read2_b32 v[50:51], v70 offset1:33
	s_and_b32 s4, s0, 0xff80
	s_and_b32 s0, s1, 0xfe0
	s_waitcnt lgkmcnt(0)
	v_cvt_pk_bf16_f32 v50, v50, v51
	ds_read2_b32 v[52:53], v70 offset0:66 offset1:99
	s_bfe_u32 s98, s0, 0x10005
	s_bfe_u32 s99, s0, 0x20006
	s_lshl_b32 s98, s98, 7
	s_lshl_b32 s99, s99, 5
	s_or_b32 s98, s98, s99
	s_andn2_b32 s99, s0, 0xe0
	s_or_b32 s98, s98, s99
	v_or_b32_e32 v4, s98, v45
	s_waitcnt lgkmcnt(0)
	v_cvt_pk_bf16_f32 v51, v52, v53
	ds_read2_b32 v[52:53], v70 offset0:132 offset1:165
	v_lshl_add_u64 v[56:57], v[30:31], 0, s[4:5]
	v_lshlrev_b32_e32 v4, 11, v4
	s_waitcnt lgkmcnt(0)
	v_cvt_pk_bf16_f32 v52, v52, v53
	ds_read2_b32 v[54:55], v70 offset0:198 offset1:231
	s_waitcnt lgkmcnt(0)
	v_cvt_pk_bf16_f32 v53, v54, v55
	v_lshl_add_u64 v[58:59], v[56:57], 0, v[4:5]
	ds_read2_b32 v[54:55], v70 offset0:8 offset1:41
	global_store_dwordx4 v[58:59], v[50:53], off
	v_or_b32_e32 v4, s98, v71
	v_lshlrev_b32_e32 v4, 11, v4
	s_waitcnt lgkmcnt(0)
	v_cvt_pk_bf16_f32 v50, v54, v55
	ds_read2_b32 v[52:53], v70 offset0:74 offset1:107
	s_waitcnt lgkmcnt(0)
	v_cvt_pk_bf16_f32 v51, v52, v53
	ds_read2_b32 v[52:53], v70 offset0:140 offset1:173
	s_waitcnt lgkmcnt(0)
	v_cvt_pk_bf16_f32 v52, v52, v53
	ds_read2_b32 v[54:55], v70 offset0:206 offset1:239
	s_waitcnt lgkmcnt(0)
	v_cvt_pk_bf16_f32 v53, v54, v55
	v_lshl_add_u64 v[58:59], v[56:57], 0, v[4:5]
	ds_read2_b32 v[54:55], v70 offset0:16 offset1:49
	global_store_dwordx4 v[58:59], v[50:53], off
	v_or_b32_e32 v4, s98, v72
	v_lshlrev_b32_e32 v4, 11, v4
	s_waitcnt lgkmcnt(0)
	v_cvt_pk_bf16_f32 v50, v54, v55
	ds_read2_b32 v[52:53], v70 offset0:82 offset1:115
	s_waitcnt lgkmcnt(0)
	v_cvt_pk_bf16_f32 v51, v52, v53
	ds_read2_b32 v[52:53], v70 offset0:148 offset1:181
	s_waitcnt lgkmcnt(0)
	v_cvt_pk_bf16_f32 v52, v52, v53
	ds_read2_b32 v[54:55], v70 offset0:214 offset1:247
	s_waitcnt lgkmcnt(0)
	v_cvt_pk_bf16_f32 v53, v54, v55
	v_lshl_add_u64 v[58:59], v[56:57], 0, v[4:5]
	ds_read2_b32 v[54:55], v70 offset0:24 offset1:57
	global_store_dwordx4 v[58:59], v[50:53], off
	v_or_b32_e32 v4, s98, v73
	v_lshlrev_b32_e32 v4, 11, v4
	s_waitcnt lgkmcnt(0)
	v_cvt_pk_bf16_f32 v50, v54, v55
	ds_read2_b32 v[52:53], v70 offset0:90 offset1:123
	s_waitcnt lgkmcnt(0)
	v_cvt_pk_bf16_f32 v51, v52, v53
	ds_read2_b32 v[52:53], v70 offset0:156 offset1:189
	s_waitcnt lgkmcnt(0)
	v_cvt_pk_bf16_f32 v52, v52, v53
	ds_read2_b32 v[54:55], v70 offset0:222 offset1:255
	s_waitcnt lgkmcnt(0)
	v_cvt_pk_bf16_f32 v53, v54, v55
	v_lshl_add_u64 v[54:55], v[56:57], 0, v[4:5]
	global_store_dwordx4 v[54:55], v[50:53], off
	s_waitcnt lgkmcnt(0)
	s_mov_b64 s[76:77], s[84:85]

.LBB0_766:
	s_lshl_b32 s5, s12, 5
	s_mov_b64 s[12:13], 0x80
	s_and_b32 s20, s5, 0x60
	s_add_i32 m0, s30, 0x18000
	v_lshl_add_u64 v[6:7], v[6:7], 0, s[12:13]
	s_lshl_b32 s15, s1, 13
	s_lshl_b32 s21, s20, 7
	s_waitcnt vmcnt(2)
	s_barrier
	global_load_lds_dwordx4 v[6:7], off
	v_lshl_add_u64 v[4:5], v[4:5], 0, s[12:13]
	s_add_i32 m0, s30, 0x1a000
	s_add_i32 s40, s30, 0x8000
	s_add_i32 s41, s30, 0xa000
	global_load_lds_dwordx4 v[4:5], off
	v_lshl_add_u64 v[0:1], v[0:1], 0, s[12:13]
	s_mov_b32 m0, s40
	s_add_u32 s18, s34, 0x40080
	global_load_lds_dwordx4 v[0:1], off
	v_lshl_add_u64 v[0:1], v[2:3], 0, s[12:13]
	s_mov_b32 m0, s41
	s_addc_u32 s19, s35, 0
	global_load_lds_dwordx4 v[0:1], off
	s_add_i32 m0, s30, 0x1c000
	v_lshl_add_u64 v[0:1], s[18:19], 0, v[130:131]
	global_load_lds_dwordx4 v[0:1], off
	v_lshl_add_u64 v[0:1], s[18:19], 0, v[134:135]
	s_add_i32 m0, s30, 0x1e000
	v_bfe_u32 v2, v192, 4, 2
	global_load_lds_dwordx4 v[0:1], off
	v_and_b32_e32 v1, 15, v192
	v_lshlrev_b32_e32 v0, 4, v2
	v_lshlrev_b32_e32 v3, 2, v192
	v_lshl_or_b32 v150, s1, 6, v1
	v_lshl_or_b32 v1, v1, 6, v0
	v_and_b32_e32 v3, 32, v3
	s_sext_i32_i8 s5, s0
	v_bitop3_b32 v4, v1, s15, v3 bitop3:0xde
	v_lshlrev_b32_e32 v1, 6, v192
	s_movk_i32 s0, 0x3c0
	v_and_or_b32 v1, v1, s0, v0
	v_bitop3_b32 v151, s21, v1, v3 bitop3:0xf6
	v_mov_b32_e32 v1, v131
	v_lshl_add_u64 v[0:1], s[56:57], 0, v[0:1]
	s_mov_b64 s[0:1], 0x400000
	v_lshl_add_u64 v[136:137], v[0:1], 0, s[0:1]
	v_lshlrev_b32_e32 v0, 8, v192
	v_and_b32_e32 v0, 0x38000, v0
	v_lshlrev_b32_e32 v1, 11, v10
	v_or3_b32 v0, v8, v0, v1
	v_add_u32_e32 v138, v0, v9
	v_lshlrev_b32_e32 v0, 4, v11
	v_and_b32_e32 v0, 0x78000, v0
	s_waitcnt vmcnt(6)
	s_cmpk_lt_u32 s14, 0x100
	v_or3_b32 v0, v8, v0, v1
	s_cselect_b64 s[14:15], -1, 0
	v_add_u32_e32 v140, v0, v9
	s_add_i32 s44, 0, 0x10000
	s_add_i32 s45, 0, 0x14000
	v_mbcnt_lo_u32_b32 v0, -1, 0
	s_ashr_i32 s42, s60, 31
	s_mov_b32 s43, s60
	s_lshl_b32 s98, s20, 1
	v_lshl_or_b32 v152, v2, 3, s98
	v_mov_b32_e32 v139, v131
	v_mov_b32_e32 v141, v131
	v_mov_b64_e32 v[142:143], 0x800
	v_mov_b64_e32 v[144:145], 0x7ff
	v_add_u32_e32 v153, s44, v151
	v_add_u32_e32 v154, s45, v151
	v_add_u32_e32 v155, 0, v4
	v_mbcnt_hi_u32_b32 v156, -1, v0
	v_mov_b32_e32 v157, 0x358637bd
	s_mov_b32 s46, 0xf800000
	v_mov_b32_e32 v158, 0x260
	s_barrier
	s_branch .LBB0_769

.LBB0_779:
	v_lshl_add_u32 v148, s4, 8, v150
	v_ashrrev_i32_e32 v149, 31, v148
	v_lshlrev_b64 v[146:147], 6, v[148:149]
	v_lshl_add_u64 v[146:147], v[136:137], 0, v[146:147]
	s_mov_b64 s[98:99], 0x2000
	global_load_dwordx4 v[160:163], v[146:147], off
	global_load_dwordx4 v[206:209], v[146:147], off offset:1024
	global_load_dwordx4 v[210:213], v[146:147], off offset:2048
	global_load_dwordx4 v[214:217], v[146:147], off offset:3072
	v_lshl_add_u64 v[234:235], v[146:147], 0, s[98:99]
	global_load_dwordx4 v[218:221], v[234:235], off
	global_load_dwordx4 v[222:225], v[234:235], off offset:1024
	global_load_dwordx4 v[226:229], v[234:235], off offset:2048
	global_load_dwordx4 v[230:233], v[234:235], off offset:3072
	v_and_b32_e32 v159, 64, v156
	v_xor_b32_e32 v147, 16, v156
	v_add_u32_e32 v167, 64, v159
	v_cmp_lt_i32_e32 vcc, v147, v167
	v_xor_b32_e32 v166, 32, v156
	v_lshl_or_b32 v146, s5, 8, v152
	v_cndmask_b32_e32 v147, v156, v147, vcc
	v_lshlrev_b32_e32 v159, 2, v147
	v_cmp_lt_i32_e32 vcc, v166, v167
	v_ashrrev_i32_e32 v147, 31, v146
	v_lshlrev_b64 v[146:147], 1, v[146:147]
	s_waitcnt vmcnt(7)
	v_mov_b32_e32 v164, v161
	v_mov_b32_e32 v165, v162
	v_mov_b32_e32 v161, v163
	v_pk_add_f32 v[160:161], v[164:165], v[160:161]
	v_lshlrev_b64 v[164:165], 13, v[148:149]
	v_add_f32_e32 v161, v160, v161
	ds_bpermute_b32 v162, v159, v161
	v_cndmask_b32_e32 v160, v156, v166, vcc
	v_lshlrev_b32_e32 v160, 2, v160
	v_lshl_add_u64 v[164:165], s[10:11], 0, v[164:165]
	v_lshl_add_u64 v[164:165], v[164:165], 0, v[146:147]
	s_waitcnt lgkmcnt(0)
	v_add_f32_e32 v161, v161, v162
	ds_bpermute_b32 v166, v160, v161
	v_or_b32_e32 v162, 16, v148
	v_ashrrev_i32_e32 v163, 31, v162
	s_waitcnt lgkmcnt(0)
	v_add_f32_e32 v149, v161, v166
	v_fmamk_f32 v149, v149, 0x3a800000, v157
	v_lshlrev_b64 v[166:167], 6, v[162:163]
	v_lshl_add_u64 v[166:167], v[136:137], 0, v[166:167]
	v_rsq_f32_e32 v161, v149
	v_mul_f32_e32 v170, 0.5, v149
	v_mul_f32_e32 v168, v161, v161
	v_fma_f32 v170, -v170, v168, 0.5
	v_fma_f32 v168, v161, v170, v161
	v_pk_mul_f32 v[126:127], v[126:127], v[168:169] op_sel_hi:[1,0]
	v_pk_mul_f32 v[124:125], v[124:125], v[168:169] op_sel_hi:[1,0]
	v_pk_mul_f32 v[122:123], v[122:123], v[168:169] op_sel_hi:[1,0]
	v_pk_mul_f32 v[120:121], v[120:121], v[168:169] op_sel_hi:[1,0]
	v_pk_mul_f32 v[114:115], v[114:115], v[168:169] op_sel_hi:[1,0]
	v_pk_mul_f32 v[112:113], v[112:113], v[168:169] op_sel_hi:[1,0]
	v_pk_mul_f32 v[118:119], v[118:119], v[168:169] op_sel_hi:[1,0]
	v_pk_mul_f32 v[116:117], v[116:117], v[168:169] op_sel_hi:[1,0]
	v_max_f32_e32 v124, 0, v124
	v_max_f32_e32 v120, 0, v120
	v_max_f32_e32 v125, 0, v125
	v_max_f32_e32 v121, 0, v121
	v_max_f32_e32 v126, 0, v126
	v_max_f32_e32 v122, 0, v122
	v_max_f32_e32 v127, 0, v127
	v_max_f32_e32 v123, 0, v123
	v_max_f32_e32 v112, 0, v112
	v_max_f32_e32 v113, 0, v113
	v_max_f32_e32 v114, 0, v114
	v_max_f32_e32 v115, 0, v115
	v_max_f32_e32 v116, 0, v116
	v_max_f32_e32 v117, 0, v117
	v_max_f32_e32 v118, 0, v118
	v_max_f32_e32 v119, 0, v119
	v_mul_f32_e32 v124, v124, v124
	v_mul_f32_e32 v120, v120, v120
	v_mul_f32_e32 v125, v125, v125
	v_mul_f32_e32 v121, v121, v121
	v_mul_f32_e32 v126, v126, v126
	v_mul_f32_e32 v122, v122, v122
	v_mul_f32_e32 v127, v127, v127
	v_mul_f32_e32 v123, v123, v123
	v_mul_f32_e32 v149, v112, v112
	v_mul_f32_e32 v161, v113, v113
	v_mul_f32_e32 v168, v114, v114
	v_mul_f32_e32 v169, v115, v115
	v_cvt_pk_bf16_f32 v112, v124, v125
	v_cvt_pk_bf16_f32 v113, v126, v127
	v_cvt_pk_bf16_f32 v114, v120, v121
	v_cvt_pk_bf16_f32 v115, v122, v123
	v_mul_f32_e32 v116, v116, v116
	v_mul_f32_e32 v117, v117, v117
	v_mul_f32_e32 v118, v118, v118
	v_mul_f32_e32 v119, v119, v119
	global_store_dwordx4 v[164:165], v[112:115], off
	s_nop 1
	v_cvt_pk_bf16_f32 v112, v116, v117
	v_cvt_pk_bf16_f32 v113, v118, v119
	v_cvt_pk_bf16_f32 v114, v149, v161
	v_cvt_pk_bf16_f32 v115, v168, v169
	global_store_dwordx4 v[164:165], v[112:115], off offset:64
	s_waitcnt vmcnt(8)
	s_nop 1
	v_mov_b32_e32 v112, v206
	v_mov_b32_e32 v113, v207
	v_mov_b32_e32 v114, v208
	v_mov_b32_e32 v115, v209
	v_mov_b32_e32 v116, v113
	v_mov_b32_e32 v117, v114
	v_mov_b32_e32 v113, v115
	v_pk_add_f32 v[112:113], v[116:117], v[112:113]
	v_lshlrev_b64 v[114:115], 13, v[162:163]
	v_add_f32_e32 v112, v112, v113
	ds_bpermute_b32 v113, v159, v112
	v_lshl_add_u64 v[114:115], s[10:11], 0, v[114:115]
	v_lshl_add_u64 v[114:115], v[114:115], 0, v[146:147]
	s_waitcnt lgkmcnt(0)
	v_add_f32_e32 v116, v112, v113
	ds_bpermute_b32 v117, v160, v116
	v_or_b32_e32 v112, 32, v148
	v_ashrrev_i32_e32 v113, 31, v112
	s_waitcnt lgkmcnt(0)
	v_add_f32_e32 v116, v116, v117
	v_fmamk_f32 v116, v116, 0x3a800000, v157
	v_mov_b32_e32 v118, v116
	v_lshlrev_b64 v[116:117], 6, v[112:113]
	v_lshl_add_u64 v[116:117], v[136:137], 0, v[116:117]
	v_rsq_f32_e32 v119, v118
	v_mul_f32_e32 v120, 0.5, v118
	v_mul_f32_e32 v118, v119, v119
	v_fma_f32 v120, -v120, v118, 0.5
	v_fma_f32 v118, v119, v120, v119
	v_pk_mul_f32 v[110:111], v[110:111], v[118:119] op_sel_hi:[1,0]
	v_pk_mul_f32 v[108:109], v[108:109], v[118:119] op_sel_hi:[1,0]
	v_pk_mul_f32 v[106:107], v[106:107], v[118:119] op_sel_hi:[1,0]
	v_pk_mul_f32 v[104:105], v[104:105], v[118:119] op_sel_hi:[1,0]
	v_pk_mul_f32 v[98:99], v[98:99], v[118:119] op_sel_hi:[1,0]
	v_pk_mul_f32 v[96:97], v[96:97], v[118:119] op_sel_hi:[1,0]
	v_pk_mul_f32 v[102:103], v[102:103], v[118:119] op_sel_hi:[1,0]
	v_pk_mul_f32 v[100:101], v[100:101], v[118:119] op_sel_hi:[1,0]
	v_max_f32_e32 v108, 0, v108
	v_max_f32_e32 v104, 0, v104
	v_max_f32_e32 v109, 0, v109
	v_max_f32_e32 v105, 0, v105
	v_max_f32_e32 v110, 0, v110
	v_max_f32_e32 v106, 0, v106
	v_max_f32_e32 v111, 0, v111
	v_max_f32_e32 v107, 0, v107
	v_max_f32_e32 v96, 0, v96
	v_max_f32_e32 v97, 0, v97
	v_max_f32_e32 v98, 0, v98
	v_max_f32_e32 v99, 0, v99
	v_max_f32_e32 v100, 0, v100
	v_max_f32_e32 v101, 0, v101
	v_max_f32_e32 v102, 0, v102
	v_max_f32_e32 v103, 0, v103
	v_mul_f32_e32 v108, v108, v108
	v_mul_f32_e32 v104, v104, v104
	v_mul_f32_e32 v109, v109, v109
	v_mul_f32_e32 v105, v105, v105
	v_mul_f32_e32 v110, v110, v110
	v_mul_f32_e32 v106, v106, v106
	v_mul_f32_e32 v111, v111, v111
	v_mul_f32_e32 v107, v107, v107
	v_mul_f32_e32 v118, v96, v96
	v_mul_f32_e32 v119, v97, v97
	v_mul_f32_e32 v120, v98, v98
	v_mul_f32_e32 v121, v99, v99
	v_cvt_pk_bf16_f32 v96, v108, v109
	v_cvt_pk_bf16_f32 v97, v110, v111
	v_cvt_pk_bf16_f32 v98, v104, v105
	v_cvt_pk_bf16_f32 v99, v106, v107
	v_mul_f32_e32 v100, v100, v100
	v_mul_f32_e32 v101, v101, v101
	v_mul_f32_e32 v102, v102, v102
	v_mul_f32_e32 v103, v103, v103
	global_store_dwordx4 v[114:115], v[96:99], off
	s_nop 1
	v_cvt_pk_bf16_f32 v96, v100, v101
	v_cvt_pk_bf16_f32 v97, v102, v103
	v_cvt_pk_bf16_f32 v98, v118, v119
	v_cvt_pk_bf16_f32 v99, v120, v121
	global_store_dwordx4 v[114:115], v[96:99], off offset:64
	s_waitcnt vmcnt(9)
	s_nop 1
	v_mov_b32_e32 v96, v210
	v_mov_b32_e32 v97, v211
	v_mov_b32_e32 v98, v212
	v_mov_b32_e32 v99, v213
	v_mov_b32_e32 v100, v97
	v_mov_b32_e32 v101, v98
	v_mov_b32_e32 v97, v99
	v_pk_add_f32 v[96:97], v[100:101], v[96:97]
	v_lshlrev_b64 v[98:99], 13, v[112:113]
	v_add_f32_e32 v96, v96, v97
	ds_bpermute_b32 v97, v159, v96
	v_lshl_add_u64 v[98:99], s[10:11], 0, v[98:99]
	v_lshl_add_u64 v[98:99], v[98:99], 0, v[146:147]
	s_waitcnt lgkmcnt(0)
	v_add_f32_e32 v100, v96, v97
	ds_bpermute_b32 v101, v160, v100
	v_or_b32_e32 v96, 48, v148
	v_ashrrev_i32_e32 v97, 31, v96
	s_waitcnt lgkmcnt(0)
	v_add_f32_e32 v100, v100, v101
	v_fmamk_f32 v100, v100, 0x3a800000, v157
	v_mov_b32_e32 v102, v100
	v_lshlrev_b64 v[100:101], 6, v[96:97]
	v_lshl_add_u64 v[100:101], v[136:137], 0, v[100:101]
	v_rsq_f32_e32 v103, v102
	v_mul_f32_e32 v104, 0.5, v102
	v_mul_f32_e32 v102, v103, v103
	v_fma_f32 v104, -v104, v102, 0.5
	v_fma_f32 v102, v103, v104, v103
	v_pk_mul_f32 v[94:95], v[94:95], v[102:103] op_sel_hi:[1,0]
	v_pk_mul_f32 v[92:93], v[92:93], v[102:103] op_sel_hi:[1,0]
	v_pk_mul_f32 v[90:91], v[90:91], v[102:103] op_sel_hi:[1,0]
	v_pk_mul_f32 v[88:89], v[88:89], v[102:103] op_sel_hi:[1,0]
	v_pk_mul_f32 v[82:83], v[82:83], v[102:103] op_sel_hi:[1,0]
	v_pk_mul_f32 v[80:81], v[80:81], v[102:103] op_sel_hi:[1,0]
	v_pk_mul_f32 v[86:87], v[86:87], v[102:103] op_sel_hi:[1,0]
	v_pk_mul_f32 v[84:85], v[84:85], v[102:103] op_sel_hi:[1,0]
	v_max_f32_e32 v92, 0, v92
	v_max_f32_e32 v88, 0, v88
	v_max_f32_e32 v93, 0, v93
	v_max_f32_e32 v89, 0, v89
	v_max_f32_e32 v94, 0, v94
	v_max_f32_e32 v90, 0, v90
	v_max_f32_e32 v95, 0, v95
	v_max_f32_e32 v91, 0, v91
	v_max_f32_e32 v80, 0, v80
	v_max_f32_e32 v81, 0, v81
	v_max_f32_e32 v82, 0, v82
	v_max_f32_e32 v83, 0, v83
	v_max_f32_e32 v84, 0, v84
	v_max_f32_e32 v85, 0, v85
	v_max_f32_e32 v86, 0, v86
	v_max_f32_e32 v87, 0, v87
	v_mul_f32_e32 v92, v92, v92
	v_mul_f32_e32 v88, v88, v88
	v_mul_f32_e32 v93, v93, v93
	v_mul_f32_e32 v89, v89, v89
	v_mul_f32_e32 v94, v94, v94
	v_mul_f32_e32 v90, v90, v90
	v_mul_f32_e32 v95, v95, v95
	v_mul_f32_e32 v91, v91, v91
	v_mul_f32_e32 v102, v80, v80
	v_mul_f32_e32 v103, v81, v81
	v_mul_f32_e32 v104, v82, v82
	v_mul_f32_e32 v105, v83, v83
	v_cvt_pk_bf16_f32 v80, v92, v93
	v_cvt_pk_bf16_f32 v81, v94, v95
	v_cvt_pk_bf16_f32 v82, v88, v89
	v_cvt_pk_bf16_f32 v83, v90, v91
	v_mul_f32_e32 v84, v84, v84
	v_mul_f32_e32 v85, v85, v85
	v_mul_f32_e32 v86, v86, v86
	v_mul_f32_e32 v87, v87, v87
	global_store_dwordx4 v[98:99], v[80:83], off
	s_nop 1
	v_cvt_pk_bf16_f32 v80, v84, v85
	v_cvt_pk_bf16_f32 v81, v86, v87
	v_cvt_pk_bf16_f32 v82, v102, v103
	v_cvt_pk_bf16_f32 v83, v104, v105
	global_store_dwordx4 v[98:99], v[80:83], off offset:64
	s_waitcnt vmcnt(10)
	s_nop 1
	v_mov_b32_e32 v80, v214
	v_mov_b32_e32 v81, v215
	v_mov_b32_e32 v82, v216
	v_mov_b32_e32 v83, v217
	v_mov_b32_e32 v84, v81
	v_mov_b32_e32 v85, v82
	v_mov_b32_e32 v81, v83
	v_pk_add_f32 v[80:81], v[84:85], v[80:81]
	v_lshlrev_b64 v[82:83], 13, v[96:97]
	v_add_f32_e32 v80, v80, v81
	ds_bpermute_b32 v81, v159, v80
	v_lshl_add_u64 v[82:83], s[10:11], 0, v[82:83]
	v_lshl_add_u64 v[82:83], v[82:83], 0, v[146:147]
	s_waitcnt lgkmcnt(0)
	v_add_f32_e32 v84, v80, v81
	ds_bpermute_b32 v85, v160, v84
	v_add_u32_e32 v80, 0x80, v148
	v_ashrrev_i32_e32 v81, 31, v80
	s_waitcnt lgkmcnt(0)
	v_add_f32_e32 v84, v84, v85
	v_fmamk_f32 v84, v84, 0x3a800000, v157
	v_mov_b32_e32 v86, v84
	v_lshlrev_b64 v[84:85], 6, v[80:81]
	v_lshl_add_u64 v[84:85], v[136:137], 0, v[84:85]
	v_rsq_f32_e32 v87, v86
	v_mul_f32_e32 v88, 0.5, v86
	v_mul_f32_e32 v86, v87, v87
	v_fma_f32 v88, -v88, v86, 0.5
	v_fma_f32 v86, v87, v88, v87
	v_pk_mul_f32 v[78:79], v[78:79], v[86:87] op_sel_hi:[1,0]
	v_pk_mul_f32 v[76:77], v[76:77], v[86:87] op_sel_hi:[1,0]
	v_pk_mul_f32 v[74:75], v[74:75], v[86:87] op_sel_hi:[1,0]
	v_pk_mul_f32 v[72:73], v[72:73], v[86:87] op_sel_hi:[1,0]
	v_pk_mul_f32 v[66:67], v[66:67], v[86:87] op_sel_hi:[1,0]
	v_pk_mul_f32 v[64:65], v[64:65], v[86:87] op_sel_hi:[1,0]
	v_pk_mul_f32 v[70:71], v[70:71], v[86:87] op_sel_hi:[1,0]
	v_pk_mul_f32 v[68:69], v[68:69], v[86:87] op_sel_hi:[1,0]
	v_max_f32_e32 v76, 0, v76
	v_max_f32_e32 v72, 0, v72
	v_max_f32_e32 v77, 0, v77
	v_max_f32_e32 v73, 0, v73
	v_max_f32_e32 v78, 0, v78
	v_max_f32_e32 v74, 0, v74
	v_max_f32_e32 v79, 0, v79
	v_max_f32_e32 v75, 0, v75
	v_max_f32_e32 v64, 0, v64
	v_max_f32_e32 v65, 0, v65
	v_max_f32_e32 v66, 0, v66
	v_max_f32_e32 v67, 0, v67
	v_max_f32_e32 v68, 0, v68
	v_max_f32_e32 v69, 0, v69
	v_max_f32_e32 v70, 0, v70
	v_max_f32_e32 v71, 0, v71
	v_mul_f32_e32 v76, v76, v76
	v_mul_f32_e32 v72, v72, v72
	v_mul_f32_e32 v77, v77, v77
	v_mul_f32_e32 v73, v73, v73
	v_mul_f32_e32 v78, v78, v78
	v_mul_f32_e32 v74, v74, v74
	v_mul_f32_e32 v79, v79, v79
	v_mul_f32_e32 v75, v75, v75
	v_mul_f32_e32 v86, v64, v64
	v_mul_f32_e32 v87, v65, v65
	v_mul_f32_e32 v88, v66, v66
	v_mul_f32_e32 v89, v67, v67
	v_cvt_pk_bf16_f32 v64, v76, v77
	v_cvt_pk_bf16_f32 v65, v78, v79
	v_cvt_pk_bf16_f32 v66, v72, v73
	v_cvt_pk_bf16_f32 v67, v74, v75
	v_mul_f32_e32 v68, v68, v68
	v_mul_f32_e32 v69, v69, v69
	v_mul_f32_e32 v70, v70, v70
	v_mul_f32_e32 v71, v71, v71
	global_store_dwordx4 v[82:83], v[64:67], off
	s_nop 1
	v_cvt_pk_bf16_f32 v64, v68, v69
	v_cvt_pk_bf16_f32 v65, v70, v71
	v_cvt_pk_bf16_f32 v66, v86, v87
	v_cvt_pk_bf16_f32 v67, v88, v89
	global_store_dwordx4 v[82:83], v[64:67], off offset:64
	s_waitcnt vmcnt(11)
	s_nop 1
	v_mov_b32_e32 v64, v218
	v_mov_b32_e32 v65, v219
	v_mov_b32_e32 v66, v220
	v_mov_b32_e32 v67, v221
	v_mov_b32_e32 v68, v65
	v_mov_b32_e32 v69, v66
	v_mov_b32_e32 v65, v67
	v_pk_add_f32 v[64:65], v[68:69], v[64:65]
	v_lshlrev_b64 v[66:67], 13, v[80:81]
	v_add_f32_e32 v64, v64, v65
	ds_bpermute_b32 v65, v159, v64
	v_lshl_add_u64 v[66:67], s[10:11], 0, v[66:67]
	v_lshl_add_u64 v[66:67], v[66:67], 0, v[146:147]
	s_waitcnt lgkmcnt(0)
	v_add_f32_e32 v68, v64, v65
	ds_bpermute_b32 v69, v160, v68
	v_add_u32_e32 v64, 0x90, v148
	v_ashrrev_i32_e32 v65, 31, v64
	s_waitcnt lgkmcnt(0)
	v_add_f32_e32 v68, v68, v69
	v_fmamk_f32 v68, v68, 0x3a800000, v157
	v_mov_b32_e32 v70, v68
	v_lshlrev_b64 v[68:69], 6, v[64:65]
	v_lshl_add_u64 v[68:69], v[136:137], 0, v[68:69]
	v_rsq_f32_e32 v71, v70
	v_mul_f32_e32 v72, 0.5, v70
	v_mul_f32_e32 v70, v71, v71
	v_fma_f32 v72, -v72, v70, 0.5
	v_fma_f32 v70, v71, v72, v71
	v_pk_mul_f32 v[62:63], v[62:63], v[70:71] op_sel_hi:[1,0]
	v_pk_mul_f32 v[60:61], v[60:61], v[70:71] op_sel_hi:[1,0]
	v_pk_mul_f32 v[58:59], v[58:59], v[70:71] op_sel_hi:[1,0]
	v_pk_mul_f32 v[56:57], v[56:57], v[70:71] op_sel_hi:[1,0]
	v_pk_mul_f32 v[50:51], v[50:51], v[70:71] op_sel_hi:[1,0]
	v_pk_mul_f32 v[48:49], v[48:49], v[70:71] op_sel_hi:[1,0]
	v_pk_mul_f32 v[54:55], v[54:55], v[70:71] op_sel_hi:[1,0]
	v_pk_mul_f32 v[52:53], v[52:53], v[70:71] op_sel_hi:[1,0]
	v_max_f32_e32 v60, 0, v60
	v_max_f32_e32 v56, 0, v56
	v_max_f32_e32 v61, 0, v61
	v_max_f32_e32 v57, 0, v57
	v_max_f32_e32 v62, 0, v62
	v_max_f32_e32 v58, 0, v58
	v_max_f32_e32 v63, 0, v63
	v_max_f32_e32 v59, 0, v59
	v_max_f32_e32 v48, 0, v48
	v_max_f32_e32 v49, 0, v49
	v_max_f32_e32 v50, 0, v50
	v_max_f32_e32 v51, 0, v51
	v_max_f32_e32 v52, 0, v52
	v_max_f32_e32 v53, 0, v53
	v_max_f32_e32 v54, 0, v54
	v_max_f32_e32 v55, 0, v55
	v_mul_f32_e32 v60, v60, v60
	v_mul_f32_e32 v56, v56, v56
	v_mul_f32_e32 v61, v61, v61
	v_mul_f32_e32 v57, v57, v57
	v_mul_f32_e32 v62, v62, v62
	v_mul_f32_e32 v58, v58, v58
	v_mul_f32_e32 v63, v63, v63
	v_mul_f32_e32 v59, v59, v59
	v_mul_f32_e32 v70, v48, v48
	v_mul_f32_e32 v71, v49, v49
	v_mul_f32_e32 v72, v50, v50
	v_mul_f32_e32 v73, v51, v51
	v_cvt_pk_bf16_f32 v48, v60, v61
	v_cvt_pk_bf16_f32 v49, v62, v63
	v_cvt_pk_bf16_f32 v50, v56, v57
	v_cvt_pk_bf16_f32 v51, v58, v59
	v_mul_f32_e32 v52, v52, v52
	v_mul_f32_e32 v53, v53, v53
	v_mul_f32_e32 v54, v54, v54
	v_mul_f32_e32 v55, v55, v55
	global_store_dwordx4 v[66:67], v[48:51], off
	s_nop 1
	v_cvt_pk_bf16_f32 v48, v52, v53
	v_cvt_pk_bf16_f32 v49, v54, v55
	v_cvt_pk_bf16_f32 v50, v70, v71
	v_cvt_pk_bf16_f32 v51, v72, v73
	global_store_dwordx4 v[66:67], v[48:51], off offset:64
	s_waitcnt vmcnt(12)
	s_nop 1
	v_mov_b32_e32 v48, v222
	v_mov_b32_e32 v49, v223
	v_mov_b32_e32 v50, v224
	v_mov_b32_e32 v51, v225
	v_mov_b32_e32 v52, v49
	v_mov_b32_e32 v53, v50
	v_mov_b32_e32 v49, v51
	v_pk_add_f32 v[48:49], v[52:53], v[48:49]
	v_lshlrev_b64 v[50:51], 13, v[64:65]
	v_add_f32_e32 v48, v48, v49
	ds_bpermute_b32 v49, v159, v48
	v_lshl_add_u64 v[50:51], s[10:11], 0, v[50:51]
	v_lshl_add_u64 v[50:51], v[50:51], 0, v[146:147]
	s_waitcnt lgkmcnt(0)
	v_add_f32_e32 v52, v48, v49
	ds_bpermute_b32 v53, v160, v52
	v_add_u32_e32 v48, 0xa0, v148
	v_ashrrev_i32_e32 v49, 31, v48
	s_waitcnt lgkmcnt(0)
	v_add_f32_e32 v52, v52, v53
	v_fmamk_f32 v52, v52, 0x3a800000, v157
	v_mov_b32_e32 v54, v52
	v_lshlrev_b64 v[52:53], 6, v[48:49]
	v_lshl_add_u64 v[52:53], v[136:137], 0, v[52:53]
	v_rsq_f32_e32 v55, v54
	v_mul_f32_e32 v56, 0.5, v54
	v_mul_f32_e32 v54, v55, v55
	v_fma_f32 v56, -v56, v54, 0.5
	v_fma_f32 v54, v55, v56, v55
	v_pk_mul_f32 v[46:47], v[46:47], v[54:55] op_sel_hi:[1,0]
	v_pk_mul_f32 v[44:45], v[44:45], v[54:55] op_sel_hi:[1,0]
	v_pk_mul_f32 v[42:43], v[42:43], v[54:55] op_sel_hi:[1,0]
	v_pk_mul_f32 v[40:41], v[40:41], v[54:55] op_sel_hi:[1,0]
	v_pk_mul_f32 v[34:35], v[34:35], v[54:55] op_sel_hi:[1,0]
	v_pk_mul_f32 v[32:33], v[32:33], v[54:55] op_sel_hi:[1,0]
	v_pk_mul_f32 v[38:39], v[38:39], v[54:55] op_sel_hi:[1,0]
	v_pk_mul_f32 v[36:37], v[36:37], v[54:55] op_sel_hi:[1,0]
	v_max_f32_e32 v44, 0, v44
	v_max_f32_e32 v40, 0, v40
	v_max_f32_e32 v45, 0, v45
	v_max_f32_e32 v41, 0, v41
	v_max_f32_e32 v46, 0, v46
	v_max_f32_e32 v42, 0, v42
	v_max_f32_e32 v47, 0, v47
	v_max_f32_e32 v43, 0, v43
	v_max_f32_e32 v32, 0, v32
	v_max_f32_e32 v33, 0, v33
	v_max_f32_e32 v34, 0, v34
	v_max_f32_e32 v35, 0, v35
	v_max_f32_e32 v36, 0, v36
	v_max_f32_e32 v37, 0, v37
	v_max_f32_e32 v38, 0, v38
	v_max_f32_e32 v39, 0, v39
	v_mul_f32_e32 v44, v44, v44
	v_mul_f32_e32 v40, v40, v40
	v_mul_f32_e32 v45, v45, v45
	v_mul_f32_e32 v41, v41, v41
	v_mul_f32_e32 v46, v46, v46
	v_mul_f32_e32 v42, v42, v42
	v_mul_f32_e32 v47, v47, v47
	v_mul_f32_e32 v43, v43, v43
	v_mul_f32_e32 v54, v32, v32
	v_mul_f32_e32 v55, v33, v33
	v_mul_f32_e32 v56, v34, v34
	v_mul_f32_e32 v57, v35, v35
	v_cvt_pk_bf16_f32 v32, v44, v45
	v_cvt_pk_bf16_f32 v33, v46, v47
	v_cvt_pk_bf16_f32 v34, v40, v41
	v_cvt_pk_bf16_f32 v35, v42, v43
	v_mul_f32_e32 v36, v36, v36
	v_mul_f32_e32 v37, v37, v37
	v_mul_f32_e32 v38, v38, v38
	v_mul_f32_e32 v39, v39, v39
	global_store_dwordx4 v[50:51], v[32:35], off
	s_nop 1
	v_cvt_pk_bf16_f32 v32, v36, v37
	v_cvt_pk_bf16_f32 v33, v38, v39
	v_cvt_pk_bf16_f32 v34, v54, v55
	v_cvt_pk_bf16_f32 v35, v56, v57
	global_store_dwordx4 v[50:51], v[32:35], off offset:64
	s_waitcnt vmcnt(13)
	s_nop 1
	v_mov_b32_e32 v32, v226
	v_mov_b32_e32 v33, v227
	v_mov_b32_e32 v34, v228
	v_mov_b32_e32 v35, v229
	v_mov_b32_e32 v36, v33
	v_mov_b32_e32 v37, v34
	v_mov_b32_e32 v33, v35
	v_pk_add_f32 v[32:33], v[36:37], v[32:33]
	v_lshlrev_b64 v[34:35], 13, v[48:49]
	v_add_f32_e32 v32, v32, v33
	ds_bpermute_b32 v33, v159, v32
	v_lshl_add_u64 v[34:35], s[10:11], 0, v[34:35]
	v_lshl_add_u64 v[34:35], v[34:35], 0, v[146:147]
	s_waitcnt lgkmcnt(0)
	v_add_f32_e32 v36, v32, v33
	ds_bpermute_b32 v37, v160, v36
	v_add_u32_e32 v32, 0xb0, v148
	v_ashrrev_i32_e32 v33, 31, v32
	s_waitcnt lgkmcnt(0)
	v_add_f32_e32 v36, v36, v37
	v_fmamk_f32 v36, v36, 0x3a800000, v157
	v_mov_b32_e32 v38, v36
	v_lshlrev_b64 v[36:37], 6, v[32:33]
	v_lshl_add_u64 v[36:37], v[136:137], 0, v[36:37]
	v_rsq_f32_e32 v39, v38
	v_mul_f32_e32 v40, 0.5, v38
	v_mul_f32_e32 v38, v39, v39
	v_fma_f32 v40, -v40, v38, 0.5
	v_fma_f32 v38, v39, v40, v39
	v_pk_mul_f32 v[30:31], v[30:31], v[38:39] op_sel_hi:[1,0]
	v_pk_mul_f32 v[28:29], v[28:29], v[38:39] op_sel_hi:[1,0]
	v_pk_mul_f32 v[26:27], v[26:27], v[38:39] op_sel_hi:[1,0]
	v_pk_mul_f32 v[24:25], v[24:25], v[38:39] op_sel_hi:[1,0]
	v_pk_mul_f32 v[18:19], v[18:19], v[38:39] op_sel_hi:[1,0]
	v_pk_mul_f32 v[16:17], v[16:17], v[38:39] op_sel_hi:[1,0]
	v_pk_mul_f32 v[22:23], v[22:23], v[38:39] op_sel_hi:[1,0]
	v_pk_mul_f32 v[20:21], v[20:21], v[38:39] op_sel_hi:[1,0]
	v_max_f32_e32 v28, 0, v28
	v_max_f32_e32 v24, 0, v24
	v_max_f32_e32 v29, 0, v29
	v_max_f32_e32 v25, 0, v25
	v_max_f32_e32 v30, 0, v30
	v_max_f32_e32 v26, 0, v26
	v_max_f32_e32 v31, 0, v31
	v_max_f32_e32 v27, 0, v27
	v_max_f32_e32 v16, 0, v16
	v_max_f32_e32 v17, 0, v17
	v_max_f32_e32 v18, 0, v18
	v_max_f32_e32 v19, 0, v19
	v_max_f32_e32 v20, 0, v20
	v_max_f32_e32 v21, 0, v21
	v_max_f32_e32 v22, 0, v22
	v_max_f32_e32 v23, 0, v23
	v_mul_f32_e32 v28, v28, v28
	v_mul_f32_e32 v24, v24, v24
	v_mul_f32_e32 v29, v29, v29
	v_mul_f32_e32 v25, v25, v25
	v_mul_f32_e32 v30, v30, v30
	v_mul_f32_e32 v26, v26, v26
	v_mul_f32_e32 v31, v31, v31
	v_mul_f32_e32 v27, v27, v27
	v_mul_f32_e32 v38, v16, v16
	v_mul_f32_e32 v39, v17, v17
	v_mul_f32_e32 v40, v18, v18
	v_mul_f32_e32 v41, v19, v19
	v_cvt_pk_bf16_f32 v16, v28, v29
	v_cvt_pk_bf16_f32 v17, v30, v31
	v_cvt_pk_bf16_f32 v18, v24, v25
	v_cvt_pk_bf16_f32 v19, v26, v27
	v_mul_f32_e32 v20, v20, v20
	v_mul_f32_e32 v21, v21, v21
	v_mul_f32_e32 v22, v22, v22
	v_mul_f32_e32 v23, v23, v23
	global_store_dwordx4 v[34:35], v[16:19], off
	s_nop 1
	v_cvt_pk_bf16_f32 v16, v20, v21
	v_cvt_pk_bf16_f32 v17, v22, v23
	v_cvt_pk_bf16_f32 v18, v38, v39
	v_cvt_pk_bf16_f32 v19, v40, v41
	global_store_dwordx4 v[34:35], v[16:19], off offset:64
	s_waitcnt vmcnt(14)
	s_nop 1
	v_mov_b32_e32 v16, v230
	v_mov_b32_e32 v17, v231
	v_mov_b32_e32 v18, v232
	v_mov_b32_e32 v19, v233
	v_mov_b32_e32 v20, v17
	v_mov_b32_e32 v21, v18
	v_mov_b32_e32 v17, v19
	v_pk_add_f32 v[16:17], v[20:21], v[16:17]
	s_nop 0
	v_add_f32_e32 v16, v16, v17
	ds_bpermute_b32 v17, v159, v16
	s_waitcnt lgkmcnt(0)
	v_add_f32_e32 v16, v16, v17
	ds_bpermute_b32 v17, v160, v16
	s_waitcnt lgkmcnt(0)
	v_add_f32_e32 v16, v16, v17
	v_fmamk_f32 v16, v16, 0x3a800000, v157
	v_mov_b32_e32 v18, v16
	v_lshlrev_b64 v[16:17], 13, v[32:33]
	v_lshl_add_u64 v[16:17], s[10:11], 0, v[16:17]
	v_lshl_add_u64 v[16:17], v[16:17], 0, v[146:147]
	v_rsq_f32_e32 v19, v18
	v_mul_f32_e32 v20, 0.5, v18
	v_mul_f32_e32 v18, v19, v19
	v_fma_f32 v20, -v20, v18, 0.5
	v_fma_f32 v18, v19, v20, v19
	v_pk_mul_f32 v[14:15], v[14:15], v[18:19] op_sel_hi:[1,0]
	v_pk_mul_f32 v[12:13], v[12:13], v[18:19] op_sel_hi:[1,0]
	v_pk_mul_f32 v[10:11], v[10:11], v[18:19] op_sel_hi:[1,0]
	v_pk_mul_f32 v[8:9], v[8:9], v[18:19] op_sel_hi:[1,0]
	v_pk_mul_f32 v[2:3], v[2:3], v[18:19] op_sel_hi:[1,0]
	v_pk_mul_f32 v[0:1], v[0:1], v[18:19] op_sel_hi:[1,0]
	v_pk_mul_f32 v[6:7], v[6:7], v[18:19] op_sel_hi:[1,0]
	v_pk_mul_f32 v[4:5], v[4:5], v[18:19] op_sel_hi:[1,0]
	v_max_f32_e32 v12, 0, v12
	v_max_f32_e32 v8, 0, v8
	v_max_f32_e32 v13, 0, v13
	v_max_f32_e32 v9, 0, v9
	v_max_f32_e32 v14, 0, v14
	v_max_f32_e32 v10, 0, v10
	v_max_f32_e32 v15, 0, v15
	v_max_f32_e32 v11, 0, v11
	v_max_f32_e32 v0, 0, v0
	v_max_f32_e32 v1, 0, v1
	v_max_f32_e32 v2, 0, v2
	v_max_f32_e32 v3, 0, v3
	s_andn2_b64 vcc, exec, s[0:1]
	v_max_f32_e32 v4, 0, v4
	v_max_f32_e32 v5, 0, v5
	v_max_f32_e32 v6, 0, v6
	v_max_f32_e32 v7, 0, v7
	v_mul_f32_e32 v12, v12, v12
	v_mul_f32_e32 v8, v8, v8
	v_mul_f32_e32 v13, v13, v13
	v_mul_f32_e32 v9, v9, v9
	v_mul_f32_e32 v14, v14, v14
	v_mul_f32_e32 v10, v10, v10
	v_mul_f32_e32 v15, v15, v15
	v_mul_f32_e32 v11, v11, v11
	v_mul_f32_e32 v18, v0, v0
	v_mul_f32_e32 v19, v1, v1
	v_mul_f32_e32 v20, v2, v2
	v_mul_f32_e32 v21, v3, v3
	v_cvt_pk_bf16_f32 v0, v12, v13
	v_cvt_pk_bf16_f32 v1, v14, v15
	v_cvt_pk_bf16_f32 v2, v8, v9
	v_cvt_pk_bf16_f32 v3, v10, v11
	s_mov_b64 s[0:1], -1
	v_mul_f32_e32 v4, v4, v4
	v_mul_f32_e32 v5, v5, v5
	v_mul_f32_e32 v6, v6, v6
	v_mul_f32_e32 v7, v7, v7
	global_store_dwordx4 v[16:17], v[0:3], off
	s_nop 1
	v_cvt_pk_bf16_f32 v0, v4, v5
	v_cvt_pk_bf16_f32 v1, v6, v7
	v_cvt_pk_bf16_f32 v2, v18, v19
	v_cvt_pk_bf16_f32 v3, v20, v21
	global_store_dwordx4 v[16:17], v[0:3], off offset:64
	s_cbranch_vccnz .LBB0_768
	s_andn2_b64 vcc, exec, s[8:9]
	s_cbranch_vccnz .LBB0_767
	s_barrier
	s_branch .LBB0_767

.LBB0_1239:
	s_lshl_b32 s5, s12, 5
	s_mov_b64 s[12:13], 0x80
	s_and_b32 s20, s5, 0x60
	s_add_i32 m0, s30, 0x18000
	v_lshl_add_u64 v[6:7], v[6:7], 0, s[12:13]
	s_lshl_b32 s15, s1, 13
	s_lshl_b32 s21, s20, 7
	s_waitcnt vmcnt(2)
	s_barrier
	global_load_lds_dwordx4 v[6:7], off
	v_lshl_add_u64 v[4:5], v[4:5], 0, s[12:13]
	s_add_i32 m0, s30, 0x1a000
	s_add_i32 s40, s30, 0x8000
	s_add_i32 s41, s30, 0xa000
	global_load_lds_dwordx4 v[4:5], off
	v_lshl_add_u64 v[0:1], v[0:1], 0, s[12:13]
	s_mov_b32 m0, s40
	s_add_u32 s18, s34, 0x40080
	global_load_lds_dwordx4 v[0:1], off
	v_lshl_add_u64 v[0:1], v[2:3], 0, s[12:13]
	s_mov_b32 m0, s41
	s_addc_u32 s19, s35, 0
	global_load_lds_dwordx4 v[0:1], off
	s_add_i32 m0, s30, 0x1c000
	v_lshl_add_u64 v[0:1], s[18:19], 0, v[130:131]
	global_load_lds_dwordx4 v[0:1], off
	v_lshl_add_u64 v[0:1], s[18:19], 0, v[134:135]
	s_add_i32 m0, s30, 0x1e000
	v_bfe_u32 v2, v192, 4, 2
	global_load_lds_dwordx4 v[0:1], off
	v_and_b32_e32 v1, 15, v192
	v_lshlrev_b32_e32 v0, 4, v2
	v_lshlrev_b32_e32 v3, 2, v192
	v_lshl_or_b32 v150, s1, 6, v1
	v_lshl_or_b32 v1, v1, 6, v0
	v_and_b32_e32 v3, 32, v3
	s_sext_i32_i8 s5, s0
	v_bitop3_b32 v4, v1, s15, v3 bitop3:0xde
	v_lshlrev_b32_e32 v1, 6, v192
	s_movk_i32 s0, 0x3c0
	v_and_or_b32 v1, v1, s0, v0
	v_bitop3_b32 v151, s21, v1, v3 bitop3:0xf6
	v_mov_b32_e32 v1, v131
	v_lshl_add_u64 v[0:1], s[56:57], 0, v[0:1]
	s_mov_b64 s[0:1], 0x800000
	v_lshl_add_u64 v[136:137], v[0:1], 0, s[0:1]
	v_lshlrev_b32_e32 v0, 8, v192
	v_and_b32_e32 v0, 0x38000, v0
	v_lshlrev_b32_e32 v1, 11, v10
	v_or3_b32 v0, v8, v0, v1
	v_add_u32_e32 v138, v0, v9
	v_lshlrev_b32_e32 v0, 4, v11
	v_and_b32_e32 v0, 0x78000, v0
	s_waitcnt vmcnt(6)
	s_cmpk_lt_u32 s14, 0x100
	v_or3_b32 v0, v8, v0, v1
	s_cselect_b64 s[14:15], -1, 0
	v_add_u32_e32 v140, v0, v9
	s_add_i32 s44, 0, 0x10000
	s_add_i32 s45, 0, 0x14000
	v_mbcnt_lo_u32_b32 v0, -1, 0
	s_ashr_i32 s42, s60, 31
	s_mov_b32 s43, s60
	s_lshl_b32 s98, s20, 1
	v_lshl_or_b32 v152, v2, 3, s98
	v_mov_b32_e32 v139, v131
	v_mov_b32_e32 v141, v131
	v_mov_b64_e32 v[142:143], 0x800
	v_mov_b64_e32 v[144:145], 0x7ff
	v_add_u32_e32 v153, s44, v151
	v_add_u32_e32 v154, s45, v151
	v_add_u32_e32 v155, 0, v4
	v_mbcnt_hi_u32_b32 v156, -1, v0
	v_mov_b32_e32 v157, 0x358637bd
	s_mov_b32 s46, 0xf800000
	v_mov_b32_e32 v158, 0x260
	s_barrier
	s_branch .LBB0_1242

.LBB0_1252:
	v_lshl_add_u32 v148, s4, 8, v150
	v_ashrrev_i32_e32 v149, 31, v148
	v_lshlrev_b64 v[146:147], 6, v[148:149]
	v_lshl_add_u64 v[146:147], v[136:137], 0, v[146:147]
	s_mov_b64 s[98:99], 0x2000
	global_load_dwordx4 v[160:163], v[146:147], off
	global_load_dwordx4 v[206:209], v[146:147], off offset:1024
	global_load_dwordx4 v[210:213], v[146:147], off offset:2048
	global_load_dwordx4 v[214:217], v[146:147], off offset:3072
	v_lshl_add_u64 v[194:195], v[146:147], 0, s[98:99]
	global_load_dwordx4 v[218:221], v[194:195], off
	global_load_dwordx4 v[222:225], v[194:195], off offset:1024
	global_load_dwordx4 v[226:229], v[194:195], off offset:2048
	global_load_dwordx4 v[230:233], v[194:195], off offset:3072
	v_and_b32_e32 v159, 64, v156
	v_xor_b32_e32 v147, 16, v156
	v_add_u32_e32 v167, 64, v159
	v_cmp_lt_i32_e32 vcc, v147, v167
	v_xor_b32_e32 v166, 32, v156
	v_lshl_or_b32 v146, s5, 8, v152
	v_cndmask_b32_e32 v147, v156, v147, vcc
	v_lshlrev_b32_e32 v159, 2, v147
	v_cmp_lt_i32_e32 vcc, v166, v167
	v_ashrrev_i32_e32 v147, 31, v146
	v_lshlrev_b64 v[146:147], 1, v[146:147]
	s_waitcnt vmcnt(7)
	v_mov_b32_e32 v164, v161
	v_mov_b32_e32 v165, v162
	v_mov_b32_e32 v161, v163
	v_pk_add_f32 v[160:161], v[164:165], v[160:161]
	v_lshlrev_b64 v[164:165], 13, v[148:149]
	v_add_f32_e32 v161, v160, v161
	ds_bpermute_b32 v162, v159, v161
	v_cndmask_b32_e32 v160, v156, v166, vcc
	v_lshlrev_b32_e32 v160, 2, v160
	v_lshl_add_u64 v[164:165], s[10:11], 0, v[164:165]
	v_lshl_add_u64 v[164:165], v[164:165], 0, v[146:147]
	s_waitcnt lgkmcnt(0)
	v_add_f32_e32 v161, v161, v162
	ds_bpermute_b32 v166, v160, v161
	v_or_b32_e32 v162, 16, v148
	v_ashrrev_i32_e32 v163, 31, v162
	s_waitcnt lgkmcnt(0)
	v_add_f32_e32 v149, v161, v166
	v_fmamk_f32 v149, v149, 0x3a800000, v157
	v_lshlrev_b64 v[166:167], 6, v[162:163]
	v_lshl_add_u64 v[166:167], v[136:137], 0, v[166:167]
	v_rsq_f32_e32 v161, v149
	v_mul_f32_e32 v170, 0.5, v149
	v_mul_f32_e32 v168, v161, v161
	v_fma_f32 v170, -v170, v168, 0.5
	v_fma_f32 v168, v161, v170, v161
	v_pk_mul_f32 v[126:127], v[126:127], v[168:169] op_sel_hi:[1,0]
	v_pk_mul_f32 v[124:125], v[124:125], v[168:169] op_sel_hi:[1,0]
	v_pk_mul_f32 v[122:123], v[122:123], v[168:169] op_sel_hi:[1,0]
	v_pk_mul_f32 v[120:121], v[120:121], v[168:169] op_sel_hi:[1,0]
	v_pk_mul_f32 v[114:115], v[114:115], v[168:169] op_sel_hi:[1,0]
	v_pk_mul_f32 v[112:113], v[112:113], v[168:169] op_sel_hi:[1,0]
	v_pk_mul_f32 v[118:119], v[118:119], v[168:169] op_sel_hi:[1,0]
	v_pk_mul_f32 v[116:117], v[116:117], v[168:169] op_sel_hi:[1,0]
	v_max_f32_e32 v124, 0, v124
	v_max_f32_e32 v120, 0, v120
	v_max_f32_e32 v125, 0, v125
	v_max_f32_e32 v121, 0, v121
	v_max_f32_e32 v126, 0, v126
	v_max_f32_e32 v122, 0, v122
	v_max_f32_e32 v127, 0, v127
	v_max_f32_e32 v123, 0, v123
	v_max_f32_e32 v112, 0, v112
	v_max_f32_e32 v113, 0, v113
	v_max_f32_e32 v114, 0, v114
	v_max_f32_e32 v115, 0, v115
	v_max_f32_e32 v116, 0, v116
	v_max_f32_e32 v117, 0, v117
	v_max_f32_e32 v118, 0, v118
	v_max_f32_e32 v119, 0, v119
	v_mul_f32_e32 v124, v124, v124
	v_mul_f32_e32 v120, v120, v120
	v_mul_f32_e32 v125, v125, v125
	v_mul_f32_e32 v121, v121, v121
	v_mul_f32_e32 v126, v126, v126
	v_mul_f32_e32 v122, v122, v122
	v_mul_f32_e32 v127, v127, v127
	v_mul_f32_e32 v123, v123, v123
	v_mul_f32_e32 v149, v112, v112
	v_mul_f32_e32 v161, v113, v113
	v_mul_f32_e32 v168, v114, v114
	v_mul_f32_e32 v169, v115, v115
	v_cvt_pk_bf16_f32 v112, v124, v125
	v_cvt_pk_bf16_f32 v113, v126, v127
	v_cvt_pk_bf16_f32 v114, v120, v121
	v_cvt_pk_bf16_f32 v115, v122, v123
	v_mul_f32_e32 v116, v116, v116
	v_mul_f32_e32 v117, v117, v117
	v_mul_f32_e32 v118, v118, v118
	v_mul_f32_e32 v119, v119, v119
	global_store_dwordx4 v[164:165], v[112:115], off
	s_nop 1
	v_cvt_pk_bf16_f32 v112, v116, v117
	v_cvt_pk_bf16_f32 v113, v118, v119
	v_cvt_pk_bf16_f32 v114, v149, v161
	v_cvt_pk_bf16_f32 v115, v168, v169
	global_store_dwordx4 v[164:165], v[112:115], off offset:64
	s_waitcnt vmcnt(8)
	s_nop 1
	v_mov_b32_e32 v112, v206
	v_mov_b32_e32 v113, v207
	v_mov_b32_e32 v114, v208
	v_mov_b32_e32 v115, v209
	v_mov_b32_e32 v116, v113
	v_mov_b32_e32 v117, v114
	v_mov_b32_e32 v113, v115
	v_pk_add_f32 v[112:113], v[116:117], v[112:113]
	v_lshlrev_b64 v[114:115], 13, v[162:163]
	v_add_f32_e32 v112, v112, v113
	ds_bpermute_b32 v113, v159, v112
	v_lshl_add_u64 v[114:115], s[10:11], 0, v[114:115]
	v_lshl_add_u64 v[114:115], v[114:115], 0, v[146:147]
	s_waitcnt lgkmcnt(0)
	v_add_f32_e32 v116, v112, v113
	ds_bpermute_b32 v117, v160, v116
	v_or_b32_e32 v112, 32, v148
	v_ashrrev_i32_e32 v113, 31, v112
	s_waitcnt lgkmcnt(0)
	v_add_f32_e32 v116, v116, v117
	v_fmamk_f32 v116, v116, 0x3a800000, v157
	v_mov_b32_e32 v118, v116
	v_lshlrev_b64 v[116:117], 6, v[112:113]
	v_lshl_add_u64 v[116:117], v[136:137], 0, v[116:117]
	v_rsq_f32_e32 v119, v118
	v_mul_f32_e32 v120, 0.5, v118
	v_mul_f32_e32 v118, v119, v119
	v_fma_f32 v120, -v120, v118, 0.5
	v_fma_f32 v118, v119, v120, v119
	v_pk_mul_f32 v[110:111], v[110:111], v[118:119] op_sel_hi:[1,0]
	v_pk_mul_f32 v[108:109], v[108:109], v[118:119] op_sel_hi:[1,0]
	v_pk_mul_f32 v[106:107], v[106:107], v[118:119] op_sel_hi:[1,0]
	v_pk_mul_f32 v[104:105], v[104:105], v[118:119] op_sel_hi:[1,0]
	v_pk_mul_f32 v[98:99], v[98:99], v[118:119] op_sel_hi:[1,0]
	v_pk_mul_f32 v[96:97], v[96:97], v[118:119] op_sel_hi:[1,0]
	v_pk_mul_f32 v[102:103], v[102:103], v[118:119] op_sel_hi:[1,0]
	v_pk_mul_f32 v[100:101], v[100:101], v[118:119] op_sel_hi:[1,0]
	v_max_f32_e32 v108, 0, v108
	v_max_f32_e32 v104, 0, v104
	v_max_f32_e32 v109, 0, v109
	v_max_f32_e32 v105, 0, v105
	v_max_f32_e32 v110, 0, v110
	v_max_f32_e32 v106, 0, v106
	v_max_f32_e32 v111, 0, v111
	v_max_f32_e32 v107, 0, v107
	v_max_f32_e32 v96, 0, v96
	v_max_f32_e32 v97, 0, v97
	v_max_f32_e32 v98, 0, v98
	v_max_f32_e32 v99, 0, v99
	v_max_f32_e32 v100, 0, v100
	v_max_f32_e32 v101, 0, v101
	v_max_f32_e32 v102, 0, v102
	v_max_f32_e32 v103, 0, v103
	v_mul_f32_e32 v108, v108, v108
	v_mul_f32_e32 v104, v104, v104
	v_mul_f32_e32 v109, v109, v109
	v_mul_f32_e32 v105, v105, v105
	v_mul_f32_e32 v110, v110, v110
	v_mul_f32_e32 v106, v106, v106
	v_mul_f32_e32 v111, v111, v111
	v_mul_f32_e32 v107, v107, v107
	v_mul_f32_e32 v118, v96, v96
	v_mul_f32_e32 v119, v97, v97
	v_mul_f32_e32 v120, v98, v98
	v_mul_f32_e32 v121, v99, v99
	v_cvt_pk_bf16_f32 v96, v108, v109
	v_cvt_pk_bf16_f32 v97, v110, v111
	v_cvt_pk_bf16_f32 v98, v104, v105
	v_cvt_pk_bf16_f32 v99, v106, v107
	v_mul_f32_e32 v100, v100, v100
	v_mul_f32_e32 v101, v101, v101
	v_mul_f32_e32 v102, v102, v102
	v_mul_f32_e32 v103, v103, v103
	global_store_dwordx4 v[114:115], v[96:99], off
	s_nop 1
	v_cvt_pk_bf16_f32 v96, v100, v101
	v_cvt_pk_bf16_f32 v97, v102, v103
	v_cvt_pk_bf16_f32 v98, v118, v119
	v_cvt_pk_bf16_f32 v99, v120, v121
	global_store_dwordx4 v[114:115], v[96:99], off offset:64
	s_waitcnt vmcnt(9)
	s_nop 1
	v_mov_b32_e32 v96, v210
	v_mov_b32_e32 v97, v211
	v_mov_b32_e32 v98, v212
	v_mov_b32_e32 v99, v213
	v_mov_b32_e32 v100, v97
	v_mov_b32_e32 v101, v98
	v_mov_b32_e32 v97, v99
	v_pk_add_f32 v[96:97], v[100:101], v[96:97]
	v_lshlrev_b64 v[98:99], 13, v[112:113]
	v_add_f32_e32 v96, v96, v97
	ds_bpermute_b32 v97, v159, v96
	v_lshl_add_u64 v[98:99], s[10:11], 0, v[98:99]
	v_lshl_add_u64 v[98:99], v[98:99], 0, v[146:147]
	s_waitcnt lgkmcnt(0)
	v_add_f32_e32 v100, v96, v97
	ds_bpermute_b32 v101, v160, v100
	v_or_b32_e32 v96, 48, v148
	v_ashrrev_i32_e32 v97, 31, v96
	s_waitcnt lgkmcnt(0)
	v_add_f32_e32 v100, v100, v101
	v_fmamk_f32 v100, v100, 0x3a800000, v157
	v_mov_b32_e32 v102, v100
	v_lshlrev_b64 v[100:101], 6, v[96:97]
	v_lshl_add_u64 v[100:101], v[136:137], 0, v[100:101]
	v_rsq_f32_e32 v103, v102
	v_mul_f32_e32 v104, 0.5, v102
	v_mul_f32_e32 v102, v103, v103
	v_fma_f32 v104, -v104, v102, 0.5
	v_fma_f32 v102, v103, v104, v103
	v_pk_mul_f32 v[94:95], v[94:95], v[102:103] op_sel_hi:[1,0]
	v_pk_mul_f32 v[92:93], v[92:93], v[102:103] op_sel_hi:[1,0]
	v_pk_mul_f32 v[90:91], v[90:91], v[102:103] op_sel_hi:[1,0]
	v_pk_mul_f32 v[88:89], v[88:89], v[102:103] op_sel_hi:[1,0]
	v_pk_mul_f32 v[82:83], v[82:83], v[102:103] op_sel_hi:[1,0]
	v_pk_mul_f32 v[80:81], v[80:81], v[102:103] op_sel_hi:[1,0]
	v_pk_mul_f32 v[86:87], v[86:87], v[102:103] op_sel_hi:[1,0]
	v_pk_mul_f32 v[84:85], v[84:85], v[102:103] op_sel_hi:[1,0]
	v_max_f32_e32 v92, 0, v92
	v_max_f32_e32 v88, 0, v88
	v_max_f32_e32 v93, 0, v93
	v_max_f32_e32 v89, 0, v89
	v_max_f32_e32 v94, 0, v94
	v_max_f32_e32 v90, 0, v90
	v_max_f32_e32 v95, 0, v95
	v_max_f32_e32 v91, 0, v91
	v_max_f32_e32 v80, 0, v80
	v_max_f32_e32 v81, 0, v81
	v_max_f32_e32 v82, 0, v82
	v_max_f32_e32 v83, 0, v83
	v_max_f32_e32 v84, 0, v84
	v_max_f32_e32 v85, 0, v85
	v_max_f32_e32 v86, 0, v86
	v_max_f32_e32 v87, 0, v87
	v_mul_f32_e32 v92, v92, v92
	v_mul_f32_e32 v88, v88, v88
	v_mul_f32_e32 v93, v93, v93
	v_mul_f32_e32 v89, v89, v89
	v_mul_f32_e32 v94, v94, v94
	v_mul_f32_e32 v90, v90, v90
	v_mul_f32_e32 v95, v95, v95
	v_mul_f32_e32 v91, v91, v91
	v_mul_f32_e32 v102, v80, v80
	v_mul_f32_e32 v103, v81, v81
	v_mul_f32_e32 v104, v82, v82
	v_mul_f32_e32 v105, v83, v83
	v_cvt_pk_bf16_f32 v80, v92, v93
	v_cvt_pk_bf16_f32 v81, v94, v95
	v_cvt_pk_bf16_f32 v82, v88, v89
	v_cvt_pk_bf16_f32 v83, v90, v91
	v_mul_f32_e32 v84, v84, v84
	v_mul_f32_e32 v85, v85, v85
	v_mul_f32_e32 v86, v86, v86
	v_mul_f32_e32 v87, v87, v87
	global_store_dwordx4 v[98:99], v[80:83], off
	s_nop 1
	v_cvt_pk_bf16_f32 v80, v84, v85
	v_cvt_pk_bf16_f32 v81, v86, v87
	v_cvt_pk_bf16_f32 v82, v102, v103
	v_cvt_pk_bf16_f32 v83, v104, v105
	global_store_dwordx4 v[98:99], v[80:83], off offset:64
	s_waitcnt vmcnt(10)
	s_nop 1
	v_mov_b32_e32 v80, v214
	v_mov_b32_e32 v81, v215
	v_mov_b32_e32 v82, v216
	v_mov_b32_e32 v83, v217
	v_mov_b32_e32 v84, v81
	v_mov_b32_e32 v85, v82
	v_mov_b32_e32 v81, v83
	v_pk_add_f32 v[80:81], v[84:85], v[80:81]
	v_lshlrev_b64 v[82:83], 13, v[96:97]
	v_add_f32_e32 v80, v80, v81
	ds_bpermute_b32 v81, v159, v80
	v_lshl_add_u64 v[82:83], s[10:11], 0, v[82:83]
	v_lshl_add_u64 v[82:83], v[82:83], 0, v[146:147]
	s_waitcnt lgkmcnt(0)
	v_add_f32_e32 v84, v80, v81
	ds_bpermute_b32 v85, v160, v84
	v_add_u32_e32 v80, 0x80, v148
	v_ashrrev_i32_e32 v81, 31, v80
	s_waitcnt lgkmcnt(0)
	v_add_f32_e32 v84, v84, v85
	v_fmamk_f32 v84, v84, 0x3a800000, v157
	v_mov_b32_e32 v86, v84
	v_lshlrev_b64 v[84:85], 6, v[80:81]
	v_lshl_add_u64 v[84:85], v[136:137], 0, v[84:85]
	v_rsq_f32_e32 v87, v86
	v_mul_f32_e32 v88, 0.5, v86
	v_mul_f32_e32 v86, v87, v87
	v_fma_f32 v88, -v88, v86, 0.5
	v_fma_f32 v86, v87, v88, v87
	v_pk_mul_f32 v[78:79], v[78:79], v[86:87] op_sel_hi:[1,0]
	v_pk_mul_f32 v[76:77], v[76:77], v[86:87] op_sel_hi:[1,0]
	v_pk_mul_f32 v[74:75], v[74:75], v[86:87] op_sel_hi:[1,0]
	v_pk_mul_f32 v[72:73], v[72:73], v[86:87] op_sel_hi:[1,0]
	v_pk_mul_f32 v[66:67], v[66:67], v[86:87] op_sel_hi:[1,0]
	v_pk_mul_f32 v[64:65], v[64:65], v[86:87] op_sel_hi:[1,0]
	v_pk_mul_f32 v[70:71], v[70:71], v[86:87] op_sel_hi:[1,0]
	v_pk_mul_f32 v[68:69], v[68:69], v[86:87] op_sel_hi:[1,0]
	v_max_f32_e32 v76, 0, v76
	v_max_f32_e32 v72, 0, v72
	v_max_f32_e32 v77, 0, v77
	v_max_f32_e32 v73, 0, v73
	v_max_f32_e32 v78, 0, v78
	v_max_f32_e32 v74, 0, v74
	v_max_f32_e32 v79, 0, v79
	v_max_f32_e32 v75, 0, v75
	v_max_f32_e32 v64, 0, v64
	v_max_f32_e32 v65, 0, v65
	v_max_f32_e32 v66, 0, v66
	v_max_f32_e32 v67, 0, v67
	v_max_f32_e32 v68, 0, v68
	v_max_f32_e32 v69, 0, v69
	v_max_f32_e32 v70, 0, v70
	v_max_f32_e32 v71, 0, v71
	v_mul_f32_e32 v76, v76, v76
	v_mul_f32_e32 v72, v72, v72
	v_mul_f32_e32 v77, v77, v77
	v_mul_f32_e32 v73, v73, v73
	v_mul_f32_e32 v78, v78, v78
	v_mul_f32_e32 v74, v74, v74
	v_mul_f32_e32 v79, v79, v79
	v_mul_f32_e32 v75, v75, v75
	v_mul_f32_e32 v86, v64, v64
	v_mul_f32_e32 v87, v65, v65
	v_mul_f32_e32 v88, v66, v66
	v_mul_f32_e32 v89, v67, v67
	v_cvt_pk_bf16_f32 v64, v76, v77
	v_cvt_pk_bf16_f32 v65, v78, v79
	v_cvt_pk_bf16_f32 v66, v72, v73
	v_cvt_pk_bf16_f32 v67, v74, v75
	v_mul_f32_e32 v68, v68, v68
	v_mul_f32_e32 v69, v69, v69
	v_mul_f32_e32 v70, v70, v70
	v_mul_f32_e32 v71, v71, v71
	global_store_dwordx4 v[82:83], v[64:67], off
	s_nop 1
	v_cvt_pk_bf16_f32 v64, v68, v69
	v_cvt_pk_bf16_f32 v65, v70, v71
	v_cvt_pk_bf16_f32 v66, v86, v87
	v_cvt_pk_bf16_f32 v67, v88, v89
	global_store_dwordx4 v[82:83], v[64:67], off offset:64
	s_waitcnt vmcnt(11)
	s_nop 1
	v_mov_b32_e32 v64, v218
	v_mov_b32_e32 v65, v219
	v_mov_b32_e32 v66, v220
	v_mov_b32_e32 v67, v221
	v_mov_b32_e32 v68, v65
	v_mov_b32_e32 v69, v66
	v_mov_b32_e32 v65, v67
	v_pk_add_f32 v[64:65], v[68:69], v[64:65]
	v_lshlrev_b64 v[66:67], 13, v[80:81]
	v_add_f32_e32 v64, v64, v65
	ds_bpermute_b32 v65, v159, v64
	v_lshl_add_u64 v[66:67], s[10:11], 0, v[66:67]
	v_lshl_add_u64 v[66:67], v[66:67], 0, v[146:147]
	s_waitcnt lgkmcnt(0)
	v_add_f32_e32 v68, v64, v65
	ds_bpermute_b32 v69, v160, v68
	v_add_u32_e32 v64, 0x90, v148
	v_ashrrev_i32_e32 v65, 31, v64
	s_waitcnt lgkmcnt(0)
	v_add_f32_e32 v68, v68, v69
	v_fmamk_f32 v68, v68, 0x3a800000, v157
	v_mov_b32_e32 v70, v68
	v_lshlrev_b64 v[68:69], 6, v[64:65]
	v_lshl_add_u64 v[68:69], v[136:137], 0, v[68:69]
	v_rsq_f32_e32 v71, v70
	v_mul_f32_e32 v72, 0.5, v70
	v_mul_f32_e32 v70, v71, v71
	v_fma_f32 v72, -v72, v70, 0.5
	v_fma_f32 v70, v71, v72, v71
	v_pk_mul_f32 v[62:63], v[62:63], v[70:71] op_sel_hi:[1,0]
	v_pk_mul_f32 v[60:61], v[60:61], v[70:71] op_sel_hi:[1,0]
	v_pk_mul_f32 v[58:59], v[58:59], v[70:71] op_sel_hi:[1,0]
	v_pk_mul_f32 v[56:57], v[56:57], v[70:71] op_sel_hi:[1,0]
	v_pk_mul_f32 v[50:51], v[50:51], v[70:71] op_sel_hi:[1,0]
	v_pk_mul_f32 v[48:49], v[48:49], v[70:71] op_sel_hi:[1,0]
	v_pk_mul_f32 v[54:55], v[54:55], v[70:71] op_sel_hi:[1,0]
	v_pk_mul_f32 v[52:53], v[52:53], v[70:71] op_sel_hi:[1,0]
	v_max_f32_e32 v60, 0, v60
	v_max_f32_e32 v56, 0, v56
	v_max_f32_e32 v61, 0, v61
	v_max_f32_e32 v57, 0, v57
	v_max_f32_e32 v62, 0, v62
	v_max_f32_e32 v58, 0, v58
	v_max_f32_e32 v63, 0, v63
	v_max_f32_e32 v59, 0, v59
	v_max_f32_e32 v48, 0, v48
	v_max_f32_e32 v49, 0, v49
	v_max_f32_e32 v50, 0, v50
	v_max_f32_e32 v51, 0, v51
	v_max_f32_e32 v52, 0, v52
	v_max_f32_e32 v53, 0, v53
	v_max_f32_e32 v54, 0, v54
	v_max_f32_e32 v55, 0, v55
	v_mul_f32_e32 v60, v60, v60
	v_mul_f32_e32 v56, v56, v56
	v_mul_f32_e32 v61, v61, v61
	v_mul_f32_e32 v57, v57, v57
	v_mul_f32_e32 v62, v62, v62
	v_mul_f32_e32 v58, v58, v58
	v_mul_f32_e32 v63, v63, v63
	v_mul_f32_e32 v59, v59, v59
	v_mul_f32_e32 v70, v48, v48
	v_mul_f32_e32 v71, v49, v49
	v_mul_f32_e32 v72, v50, v50
	v_mul_f32_e32 v73, v51, v51
	v_cvt_pk_bf16_f32 v48, v60, v61
	v_cvt_pk_bf16_f32 v49, v62, v63
	v_cvt_pk_bf16_f32 v50, v56, v57
	v_cvt_pk_bf16_f32 v51, v58, v59
	v_mul_f32_e32 v52, v52, v52
	v_mul_f32_e32 v53, v53, v53
	v_mul_f32_e32 v54, v54, v54
	v_mul_f32_e32 v55, v55, v55
	global_store_dwordx4 v[66:67], v[48:51], off
	s_nop 1
	v_cvt_pk_bf16_f32 v48, v52, v53
	v_cvt_pk_bf16_f32 v49, v54, v55
	v_cvt_pk_bf16_f32 v50, v70, v71
	v_cvt_pk_bf16_f32 v51, v72, v73
	global_store_dwordx4 v[66:67], v[48:51], off offset:64
	s_waitcnt vmcnt(12)
	s_nop 1
	v_mov_b32_e32 v48, v222
	v_mov_b32_e32 v49, v223
	v_mov_b32_e32 v50, v224
	v_mov_b32_e32 v51, v225
	v_mov_b32_e32 v52, v49
	v_mov_b32_e32 v53, v50
	v_mov_b32_e32 v49, v51
	v_pk_add_f32 v[48:49], v[52:53], v[48:49]
	v_lshlrev_b64 v[50:51], 13, v[64:65]
	v_add_f32_e32 v48, v48, v49
	ds_bpermute_b32 v49, v159, v48
	v_lshl_add_u64 v[50:51], s[10:11], 0, v[50:51]
	v_lshl_add_u64 v[50:51], v[50:51], 0, v[146:147]
	s_waitcnt lgkmcnt(0)
	v_add_f32_e32 v52, v48, v49
	ds_bpermute_b32 v53, v160, v52
	v_add_u32_e32 v48, 0xa0, v148
	v_ashrrev_i32_e32 v49, 31, v48
	s_waitcnt lgkmcnt(0)
	v_add_f32_e32 v52, v52, v53
	v_fmamk_f32 v52, v52, 0x3a800000, v157
	v_mov_b32_e32 v54, v52
	v_lshlrev_b64 v[52:53], 6, v[48:49]
	v_lshl_add_u64 v[52:53], v[136:137], 0, v[52:53]
	v_rsq_f32_e32 v55, v54
	v_mul_f32_e32 v56, 0.5, v54
	v_mul_f32_e32 v54, v55, v55
	v_fma_f32 v56, -v56, v54, 0.5
	v_fma_f32 v54, v55, v56, v55
	v_pk_mul_f32 v[46:47], v[46:47], v[54:55] op_sel_hi:[1,0]
	v_pk_mul_f32 v[44:45], v[44:45], v[54:55] op_sel_hi:[1,0]
	v_pk_mul_f32 v[42:43], v[42:43], v[54:55] op_sel_hi:[1,0]
	v_pk_mul_f32 v[40:41], v[40:41], v[54:55] op_sel_hi:[1,0]
	v_pk_mul_f32 v[34:35], v[34:35], v[54:55] op_sel_hi:[1,0]
	v_pk_mul_f32 v[32:33], v[32:33], v[54:55] op_sel_hi:[1,0]
	v_pk_mul_f32 v[38:39], v[38:39], v[54:55] op_sel_hi:[1,0]
	v_pk_mul_f32 v[36:37], v[36:37], v[54:55] op_sel_hi:[1,0]
	v_max_f32_e32 v44, 0, v44
	v_max_f32_e32 v40, 0, v40
	v_max_f32_e32 v45, 0, v45
	v_max_f32_e32 v41, 0, v41
	v_max_f32_e32 v46, 0, v46
	v_max_f32_e32 v42, 0, v42
	v_max_f32_e32 v47, 0, v47
	v_max_f32_e32 v43, 0, v43
	v_max_f32_e32 v32, 0, v32
	v_max_f32_e32 v33, 0, v33
	v_max_f32_e32 v34, 0, v34
	v_max_f32_e32 v35, 0, v35
	v_max_f32_e32 v36, 0, v36
	v_max_f32_e32 v37, 0, v37
	v_max_f32_e32 v38, 0, v38
	v_max_f32_e32 v39, 0, v39
	v_mul_f32_e32 v44, v44, v44
	v_mul_f32_e32 v40, v40, v40
	v_mul_f32_e32 v45, v45, v45
	v_mul_f32_e32 v41, v41, v41
	v_mul_f32_e32 v46, v46, v46
	v_mul_f32_e32 v42, v42, v42
	v_mul_f32_e32 v47, v47, v47
	v_mul_f32_e32 v43, v43, v43
	v_mul_f32_e32 v54, v32, v32
	v_mul_f32_e32 v55, v33, v33
	v_mul_f32_e32 v56, v34, v34
	v_mul_f32_e32 v57, v35, v35
	v_cvt_pk_bf16_f32 v32, v44, v45
	v_cvt_pk_bf16_f32 v33, v46, v47
	v_cvt_pk_bf16_f32 v34, v40, v41
	v_cvt_pk_bf16_f32 v35, v42, v43
	v_mul_f32_e32 v36, v36, v36
	v_mul_f32_e32 v37, v37, v37
	v_mul_f32_e32 v38, v38, v38
	v_mul_f32_e32 v39, v39, v39
	global_store_dwordx4 v[50:51], v[32:35], off
	s_nop 1
	v_cvt_pk_bf16_f32 v32, v36, v37
	v_cvt_pk_bf16_f32 v33, v38, v39
	v_cvt_pk_bf16_f32 v34, v54, v55
	v_cvt_pk_bf16_f32 v35, v56, v57
	global_store_dwordx4 v[50:51], v[32:35], off offset:64
	s_waitcnt vmcnt(13)
	s_nop 1
	v_mov_b32_e32 v32, v226
	v_mov_b32_e32 v33, v227
	v_mov_b32_e32 v34, v228
	v_mov_b32_e32 v35, v229
	v_mov_b32_e32 v36, v33
	v_mov_b32_e32 v37, v34
	v_mov_b32_e32 v33, v35
	v_pk_add_f32 v[32:33], v[36:37], v[32:33]
	v_lshlrev_b64 v[34:35], 13, v[48:49]
	v_add_f32_e32 v32, v32, v33
	ds_bpermute_b32 v33, v159, v32
	v_lshl_add_u64 v[34:35], s[10:11], 0, v[34:35]
	v_lshl_add_u64 v[34:35], v[34:35], 0, v[146:147]
	s_waitcnt lgkmcnt(0)
	v_add_f32_e32 v36, v32, v33
	ds_bpermute_b32 v37, v160, v36
	v_add_u32_e32 v32, 0xb0, v148
	v_ashrrev_i32_e32 v33, 31, v32
	s_waitcnt lgkmcnt(0)
	v_add_f32_e32 v36, v36, v37
	v_fmamk_f32 v36, v36, 0x3a800000, v157
	v_mov_b32_e32 v38, v36
	v_lshlrev_b64 v[36:37], 6, v[32:33]
	v_lshl_add_u64 v[36:37], v[136:137], 0, v[36:37]
	v_rsq_f32_e32 v39, v38
	v_mul_f32_e32 v40, 0.5, v38
	v_mul_f32_e32 v38, v39, v39
	v_fma_f32 v40, -v40, v38, 0.5
	v_fma_f32 v38, v39, v40, v39
	v_pk_mul_f32 v[30:31], v[30:31], v[38:39] op_sel_hi:[1,0]
	v_pk_mul_f32 v[28:29], v[28:29], v[38:39] op_sel_hi:[1,0]
	v_pk_mul_f32 v[26:27], v[26:27], v[38:39] op_sel_hi:[1,0]
	v_pk_mul_f32 v[24:25], v[24:25], v[38:39] op_sel_hi:[1,0]
	v_pk_mul_f32 v[18:19], v[18:19], v[38:39] op_sel_hi:[1,0]
	v_pk_mul_f32 v[16:17], v[16:17], v[38:39] op_sel_hi:[1,0]
	v_pk_mul_f32 v[22:23], v[22:23], v[38:39] op_sel_hi:[1,0]
	v_pk_mul_f32 v[20:21], v[20:21], v[38:39] op_sel_hi:[1,0]
	v_max_f32_e32 v28, 0, v28
	v_max_f32_e32 v24, 0, v24
	v_max_f32_e32 v29, 0, v29
	v_max_f32_e32 v25, 0, v25
	v_max_f32_e32 v30, 0, v30
	v_max_f32_e32 v26, 0, v26
	v_max_f32_e32 v31, 0, v31
	v_max_f32_e32 v27, 0, v27
	v_max_f32_e32 v16, 0, v16
	v_max_f32_e32 v17, 0, v17
	v_max_f32_e32 v18, 0, v18
	v_max_f32_e32 v19, 0, v19
	v_max_f32_e32 v20, 0, v20
	v_max_f32_e32 v21, 0, v21
	v_max_f32_e32 v22, 0, v22
	v_max_f32_e32 v23, 0, v23
	v_mul_f32_e32 v28, v28, v28
	v_mul_f32_e32 v24, v24, v24
	v_mul_f32_e32 v29, v29, v29
	v_mul_f32_e32 v25, v25, v25
	v_mul_f32_e32 v30, v30, v30
	v_mul_f32_e32 v26, v26, v26
	v_mul_f32_e32 v31, v31, v31
	v_mul_f32_e32 v27, v27, v27
	v_mul_f32_e32 v38, v16, v16
	v_mul_f32_e32 v39, v17, v17
	v_mul_f32_e32 v40, v18, v18
	v_mul_f32_e32 v41, v19, v19
	v_cvt_pk_bf16_f32 v16, v28, v29
	v_cvt_pk_bf16_f32 v17, v30, v31
	v_cvt_pk_bf16_f32 v18, v24, v25
	v_cvt_pk_bf16_f32 v19, v26, v27
	v_mul_f32_e32 v20, v20, v20
	v_mul_f32_e32 v21, v21, v21
	v_mul_f32_e32 v22, v22, v22
	v_mul_f32_e32 v23, v23, v23
	global_store_dwordx4 v[34:35], v[16:19], off
	s_nop 1
	v_cvt_pk_bf16_f32 v16, v20, v21
	v_cvt_pk_bf16_f32 v17, v22, v23
	v_cvt_pk_bf16_f32 v18, v38, v39
	v_cvt_pk_bf16_f32 v19, v40, v41
	global_store_dwordx4 v[34:35], v[16:19], off offset:64
	s_waitcnt vmcnt(14)
	s_nop 1
	v_mov_b32_e32 v16, v230
	v_mov_b32_e32 v17, v231
	v_mov_b32_e32 v18, v232
	v_mov_b32_e32 v19, v233
	v_mov_b32_e32 v20, v17
	v_mov_b32_e32 v21, v18
	v_mov_b32_e32 v17, v19
	v_pk_add_f32 v[16:17], v[20:21], v[16:17]
	s_nop 0
	v_add_f32_e32 v16, v16, v17
	ds_bpermute_b32 v17, v159, v16
	s_waitcnt lgkmcnt(0)
	v_add_f32_e32 v16, v16, v17
	ds_bpermute_b32 v17, v160, v16
	s_waitcnt lgkmcnt(0)
	v_add_f32_e32 v16, v16, v17
	v_fmamk_f32 v16, v16, 0x3a800000, v157
	v_mov_b32_e32 v18, v16
	v_lshlrev_b64 v[16:17], 13, v[32:33]
	v_lshl_add_u64 v[16:17], s[10:11], 0, v[16:17]
	v_lshl_add_u64 v[16:17], v[16:17], 0, v[146:147]
	v_rsq_f32_e32 v19, v18
	v_mul_f32_e32 v20, 0.5, v18
	v_mul_f32_e32 v18, v19, v19
	v_fma_f32 v20, -v20, v18, 0.5
	v_fma_f32 v18, v19, v20, v19
	v_pk_mul_f32 v[14:15], v[14:15], v[18:19] op_sel_hi:[1,0]
	v_pk_mul_f32 v[12:13], v[12:13], v[18:19] op_sel_hi:[1,0]
	v_pk_mul_f32 v[10:11], v[10:11], v[18:19] op_sel_hi:[1,0]
	v_pk_mul_f32 v[8:9], v[8:9], v[18:19] op_sel_hi:[1,0]
	v_pk_mul_f32 v[2:3], v[2:3], v[18:19] op_sel_hi:[1,0]
	v_pk_mul_f32 v[0:1], v[0:1], v[18:19] op_sel_hi:[1,0]
	v_pk_mul_f32 v[6:7], v[6:7], v[18:19] op_sel_hi:[1,0]
	v_pk_mul_f32 v[4:5], v[4:5], v[18:19] op_sel_hi:[1,0]
	v_max_f32_e32 v12, 0, v12
	v_max_f32_e32 v8, 0, v8
	v_max_f32_e32 v13, 0, v13
	v_max_f32_e32 v9, 0, v9
	v_max_f32_e32 v14, 0, v14
	v_max_f32_e32 v10, 0, v10
	v_max_f32_e32 v15, 0, v15
	v_max_f32_e32 v11, 0, v11
	v_max_f32_e32 v0, 0, v0
	v_max_f32_e32 v1, 0, v1
	v_max_f32_e32 v2, 0, v2
	v_max_f32_e32 v3, 0, v3
	s_andn2_b64 vcc, exec, s[0:1]
	v_max_f32_e32 v4, 0, v4
	v_max_f32_e32 v5, 0, v5
	v_max_f32_e32 v6, 0, v6
	v_max_f32_e32 v7, 0, v7
	v_mul_f32_e32 v12, v12, v12
	v_mul_f32_e32 v8, v8, v8
	v_mul_f32_e32 v13, v13, v13
	v_mul_f32_e32 v9, v9, v9
	v_mul_f32_e32 v14, v14, v14
	v_mul_f32_e32 v10, v10, v10
	v_mul_f32_e32 v15, v15, v15
	v_mul_f32_e32 v11, v11, v11
	v_mul_f32_e32 v18, v0, v0
	v_mul_f32_e32 v19, v1, v1
	v_mul_f32_e32 v20, v2, v2
	v_mul_f32_e32 v21, v3, v3
	v_cvt_pk_bf16_f32 v0, v12, v13
	v_cvt_pk_bf16_f32 v1, v14, v15
	v_cvt_pk_bf16_f32 v2, v8, v9
	v_cvt_pk_bf16_f32 v3, v10, v11
	s_mov_b64 s[0:1], -1
	v_mul_f32_e32 v4, v4, v4
	v_mul_f32_e32 v5, v5, v5
	v_mul_f32_e32 v6, v6, v6
	v_mul_f32_e32 v7, v7, v7
	global_store_dwordx4 v[16:17], v[0:3], off
	s_nop 1
	v_cvt_pk_bf16_f32 v0, v4, v5
	v_cvt_pk_bf16_f32 v1, v6, v7
	v_cvt_pk_bf16_f32 v2, v18, v19
	v_cvt_pk_bf16_f32 v3, v20, v21
	global_store_dwordx4 v[16:17], v[0:3], off offset:64
	s_cbranch_vccnz .LBB0_1241
	s_andn2_b64 vcc, exec, s[8:9]
	s_cbranch_vccnz .LBB0_1240
	s_barrier
	s_branch .LBB0_1240
